# stack on top of the permlane version: loop-invariant LDS fragment addresses hoisted out of the K-loops, counted vmcnt at the first wait of each tile and at SwiGLU/RowScale epilogue entry
# baseline (speedup 1.0000x reference)
; #define PG8_STAGE(bufoff, gbase, voff) do { _Pragma("unroll") for (int _i = 0; _i < 2; ++_i) \
;         __builtin_amdgcn_global_load_lds((const unsigned*)((const char*)(gbase) + (voff)[_i]), (PG8_LAS unsigned*)(lds + (bufoff) + ldsw + _i * 8192), 16, 0, 0); } while (0)
; #define PG8_LDA(dst, b, h) do { _Pragma("unroll") for (int m = 0; m < 4; ++m) _Pragma("unroll") for (int k = 0; k < 2; ++k) dst[m][k] = *(const PG8_LAS bf16x8*)(lds + PG8_SA(b, h) + aoff + m * 2048 + k * 1024); } while (0)
; #define PG8_LDB(dst, b, h) do { _Pragma("unroll") for (int n = 0; n < 2; ++n) _Pragma("unroll") for (int k = 0; k < 2; ++k) dst[n][k] = *(const PG8_LAS bf16x8*)(lds + PG8_SB(b, h) + boff + n * 2048 + k * 1024); } while (0)
; #define PG8_WAIT_V(n) asm volatile("s_waitcnt vmcnt(" #n ")" ::: "memory")
; #define PG8_WAIT_L(n) asm volatile("s_waitcnt lgkmcnt(" #n ")" ::: "memory")
; #define PG8_BAR __builtin_amdgcn_s_barrier()
; #define PG8_SCHED __builtin_amdgcn_sched_barrier(0)
; template <class Epi, class Sched, bool ALIGN_EPI = false, bool SP2 = false>
; __device__ __forceinline__ void gemm_phase(PG8_LAS unsigned char* lds, const Gemm g, const Sched& S, const Epi& E) {
;     ...
;         const bool has_next = S.next(ui + 1, nxt);
;         const char* nA = has_next ? (const char*)g.A + (size_t)nxt.pm * tstep : cA; const char* nB = has_next ? (const char*)g.Bt + (size_t)nxt.pn * tstep : cB;
;         for (int t = 0; t < nt; t += 2) {
;             const bool last = (t == nt - 2);
;             const char* a1 = cA + (size_t)(t + 1) * kstep;
;             const char* a2 = last ? nA : cA + (size_t)(t + 2) * kstep; const char* b2 = last ? nB : cB + (size_t)(t + 2) * kstep;
;             const char* a3 = a2 + kstep; const char* b3 = b2 + kstep;
;             if (last && has_next) S.a_ready(nxt);
;             if constexpr (SP2) {
;             PG8_LDB(B0, 0, 0); PG8_LDB(B1, 0, 1); PG8_SCHED; PG8_LDA(At, 0, 0); PG8_STAGE(PG8_SA(1, 1), a1 + hstep, voffA);
;             PG8_WAIT_V(8); PG8_WAIT_L(0); PG8_BAR; PG8_MMA(0, 0, At, B0); PG8_MMA(0, 1, At, B1); PG8_BAR; PG8_SCHED;
;             PG8_LDA(At, 0, 1); PG8_STAGE(PG8_SB(0, 0), b2, voffB); PG8_STAGE(PG8_SB(0, 1), b2 + hstep, voffB); PG8_STAGE(PG8_SA(0, 0), a2, voffA);
;             PG8_WAIT_V(8); PG8_WAIT_L(0); PG8_BAR; PG8_MMA(1, 0, At, B0); PG8_MMA(1, 1, At, B1); PG8_BAR; PG8_SCHED;
.LBB0_84:
	s_ashr_i32 s11, s10, 31
	s_lshl_b64 s[12:13], s[10:11], 20
	s_add_u32 s12, s46, s12
	s_addc_u32 s13, s47, s13
	s_and_b64 s[14:15], s[2:3], exec
	s_cselect_b32 s11, s13, s19
	s_cselect_b32 s42, s12, s18
	s_ashr_i32 s9, s8, 31
	s_lshl_b64 s[14:15], s[8:9], 20
	v_readlane_b32 s9, v255, 30
	s_add_u32 s14, s9, s14
	v_readlane_b32 s9, v255, 31
	s_addc_u32 s15, s9, s15
	s_and_b64 s[22:23], s[2:3], exec
	s_cselect_b32 s9, s15, s21
	s_cselect_b32 s44, s14, s20
	s_add_u32 s18, s18, 0x80080
	s_addc_u32 s19, s19, 0
	s_add_u32 s45, s20, 0x100
	s_addc_u32 s50, s21, 0
	s_mov_b32 s51, -2
	v_add_u32_e32 v166, 0x10000, v153
	v_add_u32_e32 v167, 0x14000, v153
	v_add_u32_e32 v248, 0x18000, v153
	v_add_u32_e32 v249, 0x1c000, v153
	s_add_u32 s20, s18, 0xfff80080
	s_addc_u32 s21, s19, -1
	s_add_i32 s56, 0, 0x10000
	s_cmp_eq_u32 s51, 28
	s_cselect_b32 s23, s11, s21
	s_cselect_b32 s22, s42, s20
	s_cselect_b32 s21, s9, s50
	s_cselect_b32 s20, s44, s45
	s_add_i32 s63, 0, 0x14000
	ds_read_b128 v[184:187], v166
	ds_read_b128 v[188:191], v166 offset:1024
	ds_read_b128 v[192:195], v166 offset:2048
	ds_read_b128 v[196:199], v166 offset:3072
	ds_read_b128 v[200:203], v167
	ds_read_b128 v[204:207], v167 offset:1024
	ds_read_b128 v[208:211], v167 offset:2048
	ds_read_b128 v[212:215], v167 offset:3072
	s_add_i32 m0, s27, 0xc000
	ds_read_b128 v[216:219], v155
	ds_read_b128 v[220:223], v155 offset:1024
	ds_read_b128 v[224:227], v155 offset:2048
	ds_read_b128 v[228:231], v155 offset:3072
	ds_read_b128 v[232:235], v155 offset:4096
	ds_read_b128 v[236:239], v155 offset:5120
	ds_read_b128 v[240:243], v155 offset:6144
	ds_read_b128 v[244:247], v155 offset:7168
	global_load_lds_dwordx4 v136, s[18:19]
	s_add_i32 m0, s27, 0xe000
	s_nop 0
	global_load_lds_dwordx4 v138, s[18:19]
	s_waitcnt vmcnt(24)
	s_waitcnt lgkmcnt(0)
	s_setprio 1
	s_barrier
	v_mfma_f32_16x16x32_bf16 v[128:131], v[184:187], v[216:219], 0
	v_mfma_f32_16x16x32_bf16 v[120:123], v[192:195], v[216:219], 0
	v_mfma_f32_16x16x32_bf16 v[112:115], v[184:187], v[224:227], 0
	v_mfma_f32_16x16x32_bf16 v[104:107], v[192:195], v[224:227], 0
	v_mfma_f32_16x16x32_bf16 v[96:99], v[184:187], v[232:235], 0
	v_mfma_f32_16x16x32_bf16 v[88:91], v[192:195], v[232:235], 0
	v_mfma_f32_16x16x32_bf16 v[80:83], v[184:187], v[240:243], 0
	v_mfma_f32_16x16x32_bf16 v[72:75], v[192:195], v[240:243], 0
	v_mfma_f32_16x16x32_bf16 v[128:131], v[188:191], v[220:223], v[128:131]
	v_mfma_f32_16x16x32_bf16 v[120:123], v[196:199], v[220:223], v[120:123]
	v_mfma_f32_16x16x32_bf16 v[112:115], v[188:191], v[228:231], v[112:115]
	v_mfma_f32_16x16x32_bf16 v[104:107], v[196:199], v[228:231], v[104:107]
	v_mfma_f32_16x16x32_bf16 v[96:99], v[188:191], v[236:239], v[96:99]
	v_mfma_f32_16x16x32_bf16 v[88:91], v[196:199], v[236:239], v[88:91]
	v_mfma_f32_16x16x32_bf16 v[80:83], v[188:191], v[244:247], v[80:83]
	v_mfma_f32_16x16x32_bf16 v[72:75], v[196:199], v[244:247], v[72:75]
	v_mfma_f32_16x16x32_bf16 v[124:127], v[200:203], v[216:219], 0
	v_mfma_f32_16x16x32_bf16 v[116:119], v[208:211], v[216:219], 0
	v_mfma_f32_16x16x32_bf16 v[108:111], v[200:203], v[224:227], 0
	v_mfma_f32_16x16x32_bf16 v[100:103], v[208:211], v[224:227], 0
	v_mfma_f32_16x16x32_bf16 v[92:95], v[200:203], v[232:235], 0
	v_mfma_f32_16x16x32_bf16 v[84:87], v[208:211], v[232:235], 0
	v_mfma_f32_16x16x32_bf16 v[76:79], v[200:203], v[240:243], 0
	v_mfma_f32_16x16x32_bf16 v[68:71], v[208:211], v[240:243], 0
	v_mfma_f32_16x16x32_bf16 v[124:127], v[204:207], v[220:223], v[124:127]
	v_mfma_f32_16x16x32_bf16 v[116:119], v[212:215], v[220:223], v[116:119]
	v_mfma_f32_16x16x32_bf16 v[108:111], v[204:207], v[228:231], v[108:111]
	v_mfma_f32_16x16x32_bf16 v[100:103], v[212:215], v[228:231], v[100:103]
	v_mfma_f32_16x16x32_bf16 v[92:95], v[204:207], v[236:239], v[92:95]
	v_mfma_f32_16x16x32_bf16 v[84:87], v[212:215], v[236:239], v[84:87]
	v_mfma_f32_16x16x32_bf16 v[76:79], v[204:207], v[244:247], v[76:79]
	v_mfma_f32_16x16x32_bf16 v[68:71], v[212:215], v[244:247], v[68:71]
	s_barrier
	s_setprio 0
	s_add_i32 s56, s56, s25
	s_mov_b32 m0, s56
	ds_read_b128 v[216:219], v155 offset:16384
	ds_read_b128 v[220:223], v155 offset:17408
	ds_read_b128 v[224:227], v155 offset:18432
	ds_read_b128 v[228:231], v155 offset:19456
	ds_read_b128 v[232:235], v155 offset:20480
	ds_read_b128 v[236:239], v155 offset:21504
	ds_read_b128 v[240:243], v155 offset:22528
	ds_read_b128 v[244:247], v155 offset:23552
	global_load_lds_dwordx4 v2, s[20:21]
	s_add_i32 m0, s56, 0x2000
	s_add_u32 s56, s20, 0x80000
	s_addc_u32 s57, s21, 0
	s_add_i32 s63, s63, s25
	global_load_lds_dwordx4 v0, s[20:21]
	s_mov_b32 m0, s63
	v_lshl_add_u64 v[252:253], s[22:23], 0, v[132:133]
	global_load_lds_dwordx4 v2, s[56:57]
	s_add_i32 m0, s63, 0x2000
	s_nop 0
	global_load_lds_dwordx4 v0, s[56:57]
	v_lshl_add_u64 v[250:251], s[22:23], 0, v[134:135]
	s_mov_b32 m0, s27
	s_nop 0
	global_load_lds_dwordx4 v[250:251], off
	s_mov_b32 m0, s28
	s_nop 0
	global_load_lds_dwordx4 v[252:253], off
	s_waitcnt vmcnt(8)
	s_waitcnt lgkmcnt(0)
	s_setprio 1
	s_barrier
; #define PG8_STAGE(bufoff, gbase, voff) do { _Pragma("unroll") for (int _i = 0; _i < 2; ++_i) \
;         __builtin_amdgcn_global_load_lds((const unsigned*)((const char*)(gbase) + (voff)[_i]), (PG8_LAS unsigned*)(lds + (bufoff) + ldsw + _i * 8192), 16, 0, 0); } while (0)
; #define PG8_LDA(dst, b, h) do { _Pragma("unroll") for (int m = 0; m < 4; ++m) _Pragma("unroll") for (int k = 0; k < 2; ++k) dst[m][k] = *(const PG8_LAS bf16x8*)(lds + PG8_SA(b, h) + aoff + m * 2048 + k * 1024); } while (0)
; #define PG8_LDB(dst, b, h) do { _Pragma("unroll") for (int n = 0; n < 2; ++n) _Pragma("unroll") for (int k = 0; k < 2; ++k) dst[n][k] = *(const PG8_LAS bf16x8*)(lds + PG8_SB(b, h) + boff + n * 2048 + k * 1024); } while (0)
; #define PG8_MMA(ai, bj, At, Bt) do { __builtin_amdgcn_s_setprio(1); _Pragma("unroll") for (int m = 0; m < 4; ++m) _Pragma("unroll") for (int n = 0; n < 2; ++n) _Pragma("unroll") for (int k = 0; k < 2; ++k) \
;         acc[ai][bj][m][n] = __builtin_amdgcn_mfma_f32_16x16x32_bf16(Bt[n][k], At[m][k], acc[ai][bj][m][n], 0, 0, 0); __builtin_amdgcn_s_setprio(0); } while (0)
; #define PG8_WAIT_V(n) asm volatile("s_waitcnt vmcnt(" #n ")" ::: "memory")
; #define PG8_WAIT_L(n) asm volatile("s_waitcnt lgkmcnt(" #n ")" ::: "memory")
; #define PG8_BAR __builtin_amdgcn_s_barrier()
; #define PG8_SCHED __builtin_amdgcn_sched_barrier(0)
; template <class Epi, class Sched, bool ALIGN_EPI = false, bool SP2 = false>
; __device__ __forceinline__ void gemm_phase(PG8_LAS unsigned char* lds, const Gemm g, const Sched& S, const Epi& E) {
;     ...
;             PG8_WAIT_V(8); PG8_WAIT_L(0); PG8_BAR; PG8_MMA(1, 0, At, B0); PG8_MMA(1, 1, At, B1); PG8_BAR; PG8_SCHED;
;             PG8_LDB(B0, 1, 0); PG8_LDB(B1, 1, 1); PG8_SCHED; PG8_LDA(At, 1, 0); PG8_STAGE(PG8_SA(0, 1), a2 + hstep, voffA);
;             PG8_WAIT_V(8); PG8_WAIT_L(0); PG8_BAR; PG8_MMA(0, 0, At, B0); PG8_MMA(0, 1, At, B1); PG8_BAR; PG8_SCHED;
	v_mfma_f32_16x16x32_bf16 v[64:67], v[184:187], v[216:219], 0
	v_mfma_f32_16x16x32_bf16 v[56:59], v[192:195], v[216:219], 0
	v_mfma_f32_16x16x32_bf16 v[48:51], v[184:187], v[224:227], 0
	v_mfma_f32_16x16x32_bf16 v[40:43], v[192:195], v[224:227], 0
	v_mfma_f32_16x16x32_bf16 v[32:35], v[184:187], v[232:235], 0
	v_mfma_f32_16x16x32_bf16 v[24:27], v[192:195], v[232:235], 0
	v_mfma_f32_16x16x32_bf16 v[16:19], v[184:187], v[240:243], 0
	v_mfma_f32_16x16x32_bf16 v[8:11], v[192:195], v[240:243], 0
	v_mfma_f32_16x16x32_bf16 v[64:67], v[188:191], v[220:223], v[64:67]
	v_mfma_f32_16x16x32_bf16 v[56:59], v[196:199], v[220:223], v[56:59]
	v_mfma_f32_16x16x32_bf16 v[48:51], v[188:191], v[228:231], v[48:51]
	v_mfma_f32_16x16x32_bf16 v[40:43], v[196:199], v[228:231], v[40:43]
	v_mfma_f32_16x16x32_bf16 v[32:35], v[188:191], v[236:239], v[32:35]
	v_mfma_f32_16x16x32_bf16 v[24:27], v[196:199], v[236:239], v[24:27]
	v_mfma_f32_16x16x32_bf16 v[16:19], v[188:191], v[244:247], v[16:19]
	v_mfma_f32_16x16x32_bf16 v[8:11], v[196:199], v[244:247], v[8:11]
	v_mfma_f32_16x16x32_bf16 v[60:63], v[200:203], v[216:219], 0
	v_mfma_f32_16x16x32_bf16 v[52:55], v[208:211], v[216:219], 0
	v_mfma_f32_16x16x32_bf16 v[44:47], v[200:203], v[224:227], 0
	v_mfma_f32_16x16x32_bf16 v[36:39], v[208:211], v[224:227], 0
	v_mfma_f32_16x16x32_bf16 v[28:31], v[200:203], v[232:235], 0
	v_mfma_f32_16x16x32_bf16 v[20:23], v[208:211], v[232:235], 0
	v_mfma_f32_16x16x32_bf16 v[12:15], v[200:203], v[240:243], 0
	v_mfma_f32_16x16x32_bf16 v[4:7], v[208:211], v[240:243], 0
	v_mfma_f32_16x16x32_bf16 v[60:63], v[204:207], v[220:223], v[60:63]
	v_mfma_f32_16x16x32_bf16 v[52:55], v[212:215], v[220:223], v[52:55]
	v_mfma_f32_16x16x32_bf16 v[44:47], v[204:207], v[228:231], v[44:47]
	v_mfma_f32_16x16x32_bf16 v[36:39], v[212:215], v[228:231], v[36:39]
	v_mfma_f32_16x16x32_bf16 v[28:31], v[204:207], v[236:239], v[28:31]
	v_mfma_f32_16x16x32_bf16 v[20:23], v[212:215], v[236:239], v[20:23]
	v_mfma_f32_16x16x32_bf16 v[12:15], v[204:207], v[244:247], v[12:15]
	v_mfma_f32_16x16x32_bf16 v[4:7], v[212:215], v[244:247], v[4:7]
	s_barrier
	s_setprio 0
	s_add_i32 s56, 0, 0x18000
	s_add_i32 s57, 0, 0x1c000
	ds_read_b128 v[184:187], v248
	ds_read_b128 v[188:191], v248 offset:1024
	ds_read_b128 v[192:195], v248 offset:2048
	ds_read_b128 v[196:199], v248 offset:3072
	ds_read_b128 v[200:203], v249
	ds_read_b128 v[204:207], v249 offset:1024
	ds_read_b128 v[208:211], v249 offset:2048
	ds_read_b128 v[212:215], v249 offset:3072
	s_add_u32 s22, s22, 0x80000
	s_addc_u32 s23, s23, 0
	s_mov_b32 m0, s29
	ds_read_b128 v[216:219], v155 offset:32768
	ds_read_b128 v[220:223], v155 offset:33792
	ds_read_b128 v[224:227], v155 offset:34816
	ds_read_b128 v[228:231], v155 offset:35840
	ds_read_b128 v[232:235], v155 offset:36864
	ds_read_b128 v[236:239], v155 offset:37888
	ds_read_b128 v[240:243], v155 offset:38912
	ds_read_b128 v[244:247], v155 offset:39936
	global_load_lds_dwordx4 v134, s[22:23]
	s_mov_b32 m0, s30
	s_nop 0
	global_load_lds_dwordx4 v132, s[22:23]
	s_waitcnt vmcnt(8)
	s_waitcnt lgkmcnt(0)
	s_setprio 1
	s_barrier
	v_mfma_f32_16x16x32_bf16 v[128:131], v[184:187], v[216:219], v[128:131]
	v_mfma_f32_16x16x32_bf16 v[120:123], v[192:195], v[216:219], v[120:123]
	v_mfma_f32_16x16x32_bf16 v[112:115], v[184:187], v[224:227], v[112:115]
	v_mfma_f32_16x16x32_bf16 v[104:107], v[192:195], v[224:227], v[104:107]
	v_mfma_f32_16x16x32_bf16 v[96:99], v[184:187], v[232:235], v[96:99]
	v_mfma_f32_16x16x32_bf16 v[88:91], v[192:195], v[232:235], v[88:91]
	v_mfma_f32_16x16x32_bf16 v[80:83], v[184:187], v[240:243], v[80:83]
	v_mfma_f32_16x16x32_bf16 v[72:75], v[192:195], v[240:243], v[72:75]
	v_mfma_f32_16x16x32_bf16 v[128:131], v[188:191], v[220:223], v[128:131]
	v_mfma_f32_16x16x32_bf16 v[120:123], v[196:199], v[220:223], v[120:123]
	v_mfma_f32_16x16x32_bf16 v[112:115], v[188:191], v[228:231], v[112:115]
	v_mfma_f32_16x16x32_bf16 v[104:107], v[196:199], v[228:231], v[104:107]
	v_mfma_f32_16x16x32_bf16 v[96:99], v[188:191], v[236:239], v[96:99]
	v_mfma_f32_16x16x32_bf16 v[88:91], v[196:199], v[236:239], v[88:91]
	v_mfma_f32_16x16x32_bf16 v[80:83], v[188:191], v[244:247], v[80:83]
	v_mfma_f32_16x16x32_bf16 v[72:75], v[196:199], v[244:247], v[72:75]
	v_mfma_f32_16x16x32_bf16 v[124:127], v[200:203], v[216:219], v[124:127]
	v_mfma_f32_16x16x32_bf16 v[116:119], v[208:211], v[216:219], v[116:119]
	v_mfma_f32_16x16x32_bf16 v[108:111], v[200:203], v[224:227], v[108:111]
	v_mfma_f32_16x16x32_bf16 v[100:103], v[208:211], v[224:227], v[100:103]
	v_mfma_f32_16x16x32_bf16 v[92:95], v[200:203], v[232:235], v[92:95]
	v_mfma_f32_16x16x32_bf16 v[84:87], v[208:211], v[232:235], v[84:87]
	v_mfma_f32_16x16x32_bf16 v[76:79], v[200:203], v[240:243], v[76:79]
	v_mfma_f32_16x16x32_bf16 v[68:71], v[208:211], v[240:243], v[68:71]
	v_mfma_f32_16x16x32_bf16 v[124:127], v[204:207], v[220:223], v[124:127]
	v_mfma_f32_16x16x32_bf16 v[116:119], v[212:215], v[220:223], v[116:119]
	v_mfma_f32_16x16x32_bf16 v[108:111], v[204:207], v[228:231], v[108:111]
	v_mfma_f32_16x16x32_bf16 v[100:103], v[212:215], v[228:231], v[100:103]
	v_mfma_f32_16x16x32_bf16 v[92:95], v[204:207], v[236:239], v[92:95]
	v_mfma_f32_16x16x32_bf16 v[84:87], v[212:215], v[236:239], v[84:87]
	v_mfma_f32_16x16x32_bf16 v[76:79], v[204:207], v[244:247], v[76:79]
	v_mfma_f32_16x16x32_bf16 v[68:71], v[212:215], v[244:247], v[68:71]
	s_barrier
; #define PG8_STAGE(bufoff, gbase, voff) do { _Pragma("unroll") for (int _i = 0; _i < 2; ++_i) \
;         __builtin_amdgcn_global_load_lds((const unsigned*)((const char*)(gbase) + (voff)[_i]), (PG8_LAS unsigned*)(lds + (bufoff) + ldsw + _i * 8192), 16, 0, 0); } while (0)
; #define PG8_LDA(dst, b, h) do { _Pragma("unroll") for (int m = 0; m < 4; ++m) _Pragma("unroll") for (int k = 0; k < 2; ++k) dst[m][k] = *(const PG8_LAS bf16x8*)(lds + PG8_SA(b, h) + aoff + m * 2048 + k * 1024); } while (0)
; #define PG8_MMA(ai, bj, At, Bt) do { __builtin_amdgcn_s_setprio(1); _Pragma("unroll") for (int m = 0; m < 4; ++m) _Pragma("unroll") for (int n = 0; n < 2; ++n) _Pragma("unroll") for (int k = 0; k < 2; ++k) \
;         acc[ai][bj][m][n] = __builtin_amdgcn_mfma_f32_16x16x32_bf16(Bt[n][k], At[m][k], acc[ai][bj][m][n], 0, 0, 0); __builtin_amdgcn_s_setprio(0); } while (0)
; #define PG8_WAIT_V(n) asm volatile("s_waitcnt vmcnt(" #n ")" ::: "memory")
; #define PG8_WAIT_L(n) asm volatile("s_waitcnt lgkmcnt(" #n ")" ::: "memory")
; #define PG8_BAR __builtin_amdgcn_s_barrier()
; #define PG8_SCHED __builtin_amdgcn_sched_barrier(0)
; template <class Epi, class Sched, bool ALIGN_EPI = false, bool SP2 = false>
; __device__ __forceinline__ void gemm_phase(PG8_LAS unsigned char* lds, const Gemm g, const Sched& S, const Epi& E) {
;     ...
;         for (int t = 0; t < nt; t += 2) {
;     ...
;             PG8_LDA(At, 1, 1); PG8_STAGE(PG8_SB(1, 0), b3, voffB); PG8_STAGE(PG8_SB(1, 1), b3 + hstep, voffB); PG8_STAGE(PG8_SA(1, 0), a3, voffA);
;             PG8_WAIT_V(8); PG8_WAIT_L(0); PG8_BAR; PG8_MMA(1, 0, At, B0); PG8_MMA(1, 1, At, B1); PG8_BAR; PG8_SCHED;
	s_setprio 0
	s_add_i32 s22, s56, s25
	s_mov_b32 m0, s22
	ds_read_b128 v[216:219], v155 offset:49152
	ds_read_b128 v[220:223], v155 offset:50176
	ds_read_b128 v[224:227], v155 offset:51200
	ds_read_b128 v[228:231], v155 offset:52224
	ds_read_b128 v[232:235], v155 offset:53248
	ds_read_b128 v[236:239], v155 offset:54272
	ds_read_b128 v[240:243], v155 offset:55296
	ds_read_b128 v[244:247], v155 offset:56320
	s_add_u32 vcc_lo, s20, 0x80
	s_addc_u32 vcc_hi, s21, 0
	global_load_lds_dwordx4 v2, vcc
	s_add_i32 m0, s22, 0x2000
	s_add_u32 s20, s20, 0x80080
	s_addc_u32 s21, s21, 0
	s_add_i32 s22, s57, s25
	s_add_u32 vcc_lo, s20, 0xfff80000
	s_addc_u32 vcc_hi, s21, -1
	global_load_lds_dwordx4 v0, vcc
	s_mov_b32 m0, s22
	s_nop 0
	global_load_lds_dwordx4 v2, s[20:21]
	s_add_i32 m0, s22, 0x2000
	s_nop 0
	global_load_lds_dwordx4 v0, s[20:21]
	v_lshl_add_u64 v[150:151], v[250:251], 0, s[36:37]
	s_mov_b32 m0, s31
	s_nop 0
	global_load_lds_dwordx4 v[150:151], off
	v_lshl_add_u64 v[150:151], v[252:253], 0, s[36:37]
	s_mov_b32 m0, s34
	s_nop 0
	global_load_lds_dwordx4 v[150:151], off
	s_waitcnt vmcnt(8)
	s_waitcnt lgkmcnt(0)
	s_setprio 1
	s_barrier
	v_mfma_f32_16x16x32_bf16 v[64:67], v[184:187], v[216:219], v[64:67]
	v_mfma_f32_16x16x32_bf16 v[56:59], v[192:195], v[216:219], v[56:59]
	v_mfma_f32_16x16x32_bf16 v[48:51], v[184:187], v[224:227], v[48:51]
	v_mfma_f32_16x16x32_bf16 v[40:43], v[192:195], v[224:227], v[40:43]
	v_mfma_f32_16x16x32_bf16 v[32:35], v[184:187], v[232:235], v[32:35]
	v_mfma_f32_16x16x32_bf16 v[24:27], v[192:195], v[232:235], v[24:27]
	v_mfma_f32_16x16x32_bf16 v[16:19], v[184:187], v[240:243], v[16:19]
	v_mfma_f32_16x16x32_bf16 v[8:11], v[192:195], v[240:243], v[8:11]
	v_mfma_f32_16x16x32_bf16 v[64:67], v[188:191], v[220:223], v[64:67]
	v_mfma_f32_16x16x32_bf16 v[56:59], v[196:199], v[220:223], v[56:59]
	v_mfma_f32_16x16x32_bf16 v[48:51], v[188:191], v[228:231], v[48:51]
	v_mfma_f32_16x16x32_bf16 v[40:43], v[196:199], v[228:231], v[40:43]
	v_mfma_f32_16x16x32_bf16 v[32:35], v[188:191], v[236:239], v[32:35]
	v_mfma_f32_16x16x32_bf16 v[24:27], v[196:199], v[236:239], v[24:27]
	v_mfma_f32_16x16x32_bf16 v[16:19], v[188:191], v[244:247], v[16:19]
	v_mfma_f32_16x16x32_bf16 v[8:11], v[196:199], v[244:247], v[8:11]
	v_mfma_f32_16x16x32_bf16 v[60:63], v[200:203], v[216:219], v[60:63]
	v_mfma_f32_16x16x32_bf16 v[52:55], v[208:211], v[216:219], v[52:55]
	v_mfma_f32_16x16x32_bf16 v[44:47], v[200:203], v[224:227], v[44:47]
	v_mfma_f32_16x16x32_bf16 v[36:39], v[208:211], v[224:227], v[36:39]
	v_mfma_f32_16x16x32_bf16 v[28:31], v[200:203], v[232:235], v[28:31]
	v_mfma_f32_16x16x32_bf16 v[20:23], v[208:211], v[232:235], v[20:23]
	v_mfma_f32_16x16x32_bf16 v[12:15], v[200:203], v[240:243], v[12:15]
	v_mfma_f32_16x16x32_bf16 v[4:7], v[208:211], v[240:243], v[4:7]
	v_mfma_f32_16x16x32_bf16 v[60:63], v[204:207], v[220:223], v[60:63]
	v_mfma_f32_16x16x32_bf16 v[52:55], v[212:215], v[220:223], v[52:55]
	v_mfma_f32_16x16x32_bf16 v[44:47], v[204:207], v[228:231], v[44:47]
	v_mfma_f32_16x16x32_bf16 v[36:39], v[212:215], v[228:231], v[36:39]
	v_mfma_f32_16x16x32_bf16 v[28:31], v[204:207], v[236:239], v[28:31]
	v_mfma_f32_16x16x32_bf16 v[20:23], v[212:215], v[236:239], v[20:23]
	v_mfma_f32_16x16x32_bf16 v[12:15], v[204:207], v[244:247], v[12:15]
	v_mfma_f32_16x16x32_bf16 v[4:7], v[212:215], v[244:247], v[4:7]
	s_barrier
	s_setprio 0
	s_add_i32 s51, s51, 2
	s_add_u32 s18, s18, 0x100
	s_addc_u32 s19, s19, 0
	s_add_u32 s45, s45, 0x100
	s_addc_u32 s50, s50, 0
	s_cmp_gt_u32 s51, 29

; #define PG8_STAGE(bufoff, gbase, voff) do { _Pragma("unroll") for (int _i = 0; _i < 2; ++_i) \
;         __builtin_amdgcn_global_load_lds((const unsigned*)((const char*)(gbase) + (voff)[_i]), (PG8_LAS unsigned*)(lds + (bufoff) + ldsw + _i * 8192), 16, 0, 0); } while (0)
; #define PG8_LDA(dst, b, h) do { _Pragma("unroll") for (int m = 0; m < 4; ++m) _Pragma("unroll") for (int k = 0; k < 2; ++k) dst[m][k] = *(const PG8_LAS bf16x8*)(lds + PG8_SA(b, h) + aoff + m * 2048 + k * 1024); } while (0)
; #define PG8_LDB(dst, b, h) do { _Pragma("unroll") for (int n = 0; n < 2; ++n) _Pragma("unroll") for (int k = 0; k < 2; ++k) dst[n][k] = *(const PG8_LAS bf16x8*)(lds + PG8_SB(b, h) + boff + n * 2048 + k * 1024); } while (0)
; #define PG8_WAIT_V(n) asm volatile("s_waitcnt vmcnt(" #n ")" ::: "memory")
; #define PG8_WAIT_L(n) asm volatile("s_waitcnt lgkmcnt(" #n ")" ::: "memory")
; #define PG8_BAR __builtin_amdgcn_s_barrier()
; #define PG8_SCHED __builtin_amdgcn_sched_barrier(0)
; template <class Epi, class Sched, bool ALIGN_EPI = false, bool SP2 = false>
; __device__ __forceinline__ void gemm_phase(PG8_LAS unsigned char* lds, const Gemm g, const Sched& S, const Epi& E) {
;     ...
;         const char* nA = has_next ? (const char*)g.A + (size_t)nxt.pm * tstep : cA; const char* nB = has_next ? (const char*)g.Bt + (size_t)nxt.pn * tstep : cB;
;         for (int t = 0; t < nt; t += 2) {
;             const bool last = (t == nt - 2);
;             const char* a1 = cA + (size_t)(t + 1) * kstep;
;             const char* a2 = last ? nA : cA + (size_t)(t + 2) * kstep; const char* b2 = last ? nB : cB + (size_t)(t + 2) * kstep;
;             const char* a3 = a2 + kstep; const char* b3 = b2 + kstep;
;             if (last && has_next) S.a_ready(nxt);
;             if constexpr (SP2) {
;             PG8_LDB(B0, 0, 0); PG8_LDB(B1, 0, 1); PG8_SCHED; PG8_LDA(At, 0, 0); PG8_STAGE(PG8_SA(1, 1), a1 + hstep, voffA);
;             PG8_WAIT_V(8); PG8_WAIT_L(0); PG8_BAR; PG8_MMA(0, 0, At, B0); PG8_MMA(0, 1, At, B1); PG8_BAR; PG8_SCHED;
;             PG8_LDA(At, 0, 1); PG8_STAGE(PG8_SB(0, 0), b2, voffB); PG8_STAGE(PG8_SB(0, 1), b2 + hstep, voffB); PG8_STAGE(PG8_SA(0, 0), a2, voffA);
;             PG8_WAIT_V(8); PG8_WAIT_L(0); PG8_BAR; PG8_MMA(1, 0, At, B0); PG8_MMA(1, 1, At, B1); PG8_BAR; PG8_SCHED;
.LBB0_166:
	s_add_u32 s51, s16, 0x100
	s_addc_u32 s56, s17, 0
	s_mov_b32 s57, -2
	s_waitcnt lgkmcnt(0)
	v_add_u32_e32 v238, 0x10000, v185
	v_add_u32_e32 v239, 0x14000, v185
	v_add_u32_e32 v240, 0x18000, v185
	v_add_u32_e32 v241, 0x1c000, v185
	s_add_u32 s16, s14, 0x100
	s_addc_u32 s17, s15, 0
	s_add_i32 s63, 0, 0x10000
	s_cmpk_eq_i32 s57, 0x54
	s_cselect_b32 s21, s7, s17
	s_cselect_b32 s20, s6, s16
	s_cselect_b32 s19, s13, s56
	s_cselect_b32 s18, s12, s51
	s_add_i32 s64, 0, 0x14000
	ds_read_b128 v[132:135], v238
	ds_read_b128 v[136:139], v238 offset:1024
	ds_read_b128 v[158:161], v238 offset:2048
	ds_read_b128 v[162:165], v238 offset:3072
	ds_read_b128 v[188:191], v239
	ds_read_b128 v[192:195], v239 offset:1024
	ds_read_b128 v[196:199], v239 offset:2048
	ds_read_b128 v[200:203], v239 offset:3072
	s_add_i32 m0, s26, 0xc000
	ds_read_b128 v[204:207], v187
	ds_read_b128 v[208:211], v187 offset:1024
	ds_read_b128 v[212:215], v187 offset:2048
	ds_read_b128 v[216:219], v187 offset:3072
	ds_read_b128 v[220:223], v187 offset:4096
	ds_read_b128 v[224:227], v187 offset:5120
	ds_read_b128 v[228:231], v187 offset:6144
	ds_read_b128 v[232:235], v187 offset:7168
	global_load_lds_dwordx4 v154, s[14:15]
	s_add_i32 m0, s26, 0xe000
	s_nop 0
	global_load_lds_dwordx4 v156, s[14:15]
	s_waitcnt vmcnt(24)
	s_waitcnt lgkmcnt(0)
	s_setprio 1
	s_barrier
	v_mfma_f32_16x16x32_bf16 v[128:131], v[132:135], v[204:207], 0
	v_mfma_f32_16x16x32_bf16 v[124:127], v[158:161], v[204:207], 0
	v_mfma_f32_16x16x32_bf16 v[112:115], v[132:135], v[212:215], 0
	v_mfma_f32_16x16x32_bf16 v[108:111], v[158:161], v[212:215], 0
	v_mfma_f32_16x16x32_bf16 v[96:99], v[132:135], v[220:223], 0
	v_mfma_f32_16x16x32_bf16 v[92:95], v[158:161], v[220:223], 0
	v_mfma_f32_16x16x32_bf16 v[80:83], v[132:135], v[228:231], 0
	v_mfma_f32_16x16x32_bf16 v[76:79], v[158:161], v[228:231], 0
	v_mfma_f32_16x16x32_bf16 v[128:131], v[136:139], v[208:211], v[128:131]
	v_mfma_f32_16x16x32_bf16 v[124:127], v[162:165], v[208:211], v[124:127]
	v_mfma_f32_16x16x32_bf16 v[112:115], v[136:139], v[216:219], v[112:115]
	v_mfma_f32_16x16x32_bf16 v[108:111], v[162:165], v[216:219], v[108:111]
	v_mfma_f32_16x16x32_bf16 v[96:99], v[136:139], v[224:227], v[96:99]
	v_mfma_f32_16x16x32_bf16 v[92:95], v[162:165], v[224:227], v[92:95]
	v_mfma_f32_16x16x32_bf16 v[80:83], v[136:139], v[232:235], v[80:83]
	v_mfma_f32_16x16x32_bf16 v[76:79], v[162:165], v[232:235], v[76:79]
	v_mfma_f32_16x16x32_bf16 v[120:123], v[188:191], v[204:207], 0
	v_mfma_f32_16x16x32_bf16 v[116:119], v[196:199], v[204:207], 0
	v_mfma_f32_16x16x32_bf16 v[104:107], v[188:191], v[212:215], 0
	v_mfma_f32_16x16x32_bf16 v[100:103], v[196:199], v[212:215], 0
	v_mfma_f32_16x16x32_bf16 v[88:91], v[188:191], v[220:223], 0
	v_mfma_f32_16x16x32_bf16 v[84:87], v[196:199], v[220:223], 0
	v_mfma_f32_16x16x32_bf16 v[72:75], v[188:191], v[228:231], 0
	v_mfma_f32_16x16x32_bf16 v[68:71], v[196:199], v[228:231], 0
	v_mfma_f32_16x16x32_bf16 v[120:123], v[192:195], v[208:211], v[120:123]
	v_mfma_f32_16x16x32_bf16 v[116:119], v[200:203], v[208:211], v[116:119]
	v_mfma_f32_16x16x32_bf16 v[104:107], v[192:195], v[216:219], v[104:107]
	v_mfma_f32_16x16x32_bf16 v[100:103], v[200:203], v[216:219], v[100:103]
	v_mfma_f32_16x16x32_bf16 v[88:91], v[192:195], v[224:227], v[88:91]
	v_mfma_f32_16x16x32_bf16 v[84:87], v[200:203], v[224:227], v[84:87]
	v_mfma_f32_16x16x32_bf16 v[72:75], v[192:195], v[232:235], v[72:75]
	v_mfma_f32_16x16x32_bf16 v[68:71], v[200:203], v[232:235], v[68:71]
	s_barrier
	s_setprio 0
	s_add_i32 s14, s63, s25
	s_mov_b32 m0, s14
	ds_read_b128 v[204:207], v187 offset:16384
	ds_read_b128 v[208:211], v187 offset:17408
	ds_read_b128 v[212:215], v187 offset:18432
	ds_read_b128 v[216:219], v187 offset:19456
	ds_read_b128 v[220:223], v187 offset:20480
	ds_read_b128 v[224:227], v187 offset:21504
	ds_read_b128 v[228:231], v187 offset:22528
	ds_read_b128 v[232:235], v187 offset:23552
	global_load_lds_dwordx4 v2, s[18:19]
	s_add_i32 m0, s14, 0x2000
	s_add_u32 s14, s18, 0x160000
	v_lshl_add_u64 v[236:237], s[18:19], 0, v[152:153]
	s_addc_u32 s15, s19, 0
	s_add_i32 s63, s64, s25
	global_load_lds_dwordx4 v[236:237], off
	s_mov_b32 m0, s63
	s_nop 0
	global_load_lds_dwordx4 v2, s[14:15]
	s_add_i32 m0, s63, 0x2000
	s_nop 0
	global_load_lds_dwordx4 v152, s[14:15]
	s_mov_b32 m0, s26
	s_nop 0
	global_load_lds_dwordx4 v0, s[20:21]
	s_mov_b32 m0, s27
	s_nop 0
	global_load_lds_dwordx4 v150, s[20:21]
	s_waitcnt vmcnt(8)
	s_waitcnt lgkmcnt(0)
	s_setprio 1
	s_barrier
	v_mfma_f32_16x16x32_bf16 v[64:67], v[132:135], v[204:207], 0
	v_mfma_f32_16x16x32_bf16 v[60:63], v[158:161], v[204:207], 0
	v_mfma_f32_16x16x32_bf16 v[48:51], v[132:135], v[212:215], 0
	v_mfma_f32_16x16x32_bf16 v[44:47], v[158:161], v[212:215], 0
	v_mfma_f32_16x16x32_bf16 v[32:35], v[132:135], v[220:223], 0
	v_mfma_f32_16x16x32_bf16 v[28:31], v[158:161], v[220:223], 0
	v_mfma_f32_16x16x32_bf16 v[16:19], v[132:135], v[228:231], 0
	v_mfma_f32_16x16x32_bf16 v[12:15], v[158:161], v[228:231], 0
	v_mfma_f32_16x16x32_bf16 v[64:67], v[136:139], v[208:211], v[64:67]
	v_mfma_f32_16x16x32_bf16 v[60:63], v[162:165], v[208:211], v[60:63]
	v_mfma_f32_16x16x32_bf16 v[48:51], v[136:139], v[216:219], v[48:51]
	v_mfma_f32_16x16x32_bf16 v[44:47], v[162:165], v[216:219], v[44:47]
	v_mfma_f32_16x16x32_bf16 v[32:35], v[136:139], v[224:227], v[32:35]
	v_mfma_f32_16x16x32_bf16 v[28:31], v[162:165], v[224:227], v[28:31]
	v_mfma_f32_16x16x32_bf16 v[16:19], v[136:139], v[232:235], v[16:19]
	v_mfma_f32_16x16x32_bf16 v[12:15], v[162:165], v[232:235], v[12:15]
	v_mfma_f32_16x16x32_bf16 v[56:59], v[188:191], v[204:207], 0
	v_mfma_f32_16x16x32_bf16 v[52:55], v[196:199], v[204:207], 0
	v_mfma_f32_16x16x32_bf16 v[40:43], v[188:191], v[212:215], 0
	v_mfma_f32_16x16x32_bf16 v[36:39], v[196:199], v[212:215], 0
	v_mfma_f32_16x16x32_bf16 v[24:27], v[188:191], v[220:223], 0
	v_mfma_f32_16x16x32_bf16 v[20:23], v[196:199], v[220:223], 0
	v_mfma_f32_16x16x32_bf16 v[8:11], v[188:191], v[228:231], 0
	v_mfma_f32_16x16x32_bf16 v[4:7], v[196:199], v[228:231], 0
	v_mfma_f32_16x16x32_bf16 v[56:59], v[192:195], v[208:211], v[56:59]
	v_mfma_f32_16x16x32_bf16 v[52:55], v[200:203], v[208:211], v[52:55]
	v_mfma_f32_16x16x32_bf16 v[40:43], v[192:195], v[216:219], v[40:43]
	v_mfma_f32_16x16x32_bf16 v[36:39], v[200:203], v[216:219], v[36:39]
	v_mfma_f32_16x16x32_bf16 v[24:27], v[192:195], v[224:227], v[24:27]
	v_mfma_f32_16x16x32_bf16 v[20:23], v[200:203], v[224:227], v[20:23]
	v_mfma_f32_16x16x32_bf16 v[8:11], v[192:195], v[232:235], v[8:11]
	v_mfma_f32_16x16x32_bf16 v[4:7], v[200:203], v[232:235], v[4:7]
	s_barrier
; #define PG8_STAGE(bufoff, gbase, voff) do { _Pragma("unroll") for (int _i = 0; _i < 2; ++_i) \
;         __builtin_amdgcn_global_load_lds((const unsigned*)((const char*)(gbase) + (voff)[_i]), (PG8_LAS unsigned*)(lds + (bufoff) + ldsw + _i * 8192), 16, 0, 0); } while (0)
; #define PG8_LDA(dst, b, h) do { _Pragma("unroll") for (int m = 0; m < 4; ++m) _Pragma("unroll") for (int k = 0; k < 2; ++k) dst[m][k] = *(const PG8_LAS bf16x8*)(lds + PG8_SA(b, h) + aoff + m * 2048 + k * 1024); } while (0)
; #define PG8_LDB(dst, b, h) do { _Pragma("unroll") for (int n = 0; n < 2; ++n) _Pragma("unroll") for (int k = 0; k < 2; ++k) dst[n][k] = *(const PG8_LAS bf16x8*)(lds + PG8_SB(b, h) + boff + n * 2048 + k * 1024); } while (0)
; #define PG8_MMA(ai, bj, At, Bt) do { __builtin_amdgcn_s_setprio(1); _Pragma("unroll") for (int m = 0; m < 4; ++m) _Pragma("unroll") for (int n = 0; n < 2; ++n) _Pragma("unroll") for (int k = 0; k < 2; ++k) \
;         acc[ai][bj][m][n] = __builtin_amdgcn_mfma_f32_16x16x32_bf16(Bt[n][k], At[m][k], acc[ai][bj][m][n], 0, 0, 0); __builtin_amdgcn_s_setprio(0); } while (0)
; #define PG8_WAIT_V(n) asm volatile("s_waitcnt vmcnt(" #n ")" ::: "memory")
; #define PG8_WAIT_L(n) asm volatile("s_waitcnt lgkmcnt(" #n ")" ::: "memory")
; #define PG8_BAR __builtin_amdgcn_s_barrier()
; #define PG8_SCHED __builtin_amdgcn_sched_barrier(0)
; template <class Epi, class Sched, bool ALIGN_EPI = false, bool SP2 = false>
; __device__ __forceinline__ void gemm_phase(PG8_LAS unsigned char* lds, const Gemm g, const Sched& S, const Epi& E) {
;     ...
;             PG8_LDB(B0, 1, 0); PG8_LDB(B1, 1, 1); PG8_SCHED; PG8_LDA(At, 1, 0); PG8_STAGE(PG8_SA(0, 1), a2 + hstep, voffA);
;             PG8_WAIT_V(8); PG8_WAIT_L(0); PG8_BAR; PG8_MMA(0, 0, At, B0); PG8_MMA(0, 1, At, B1); PG8_BAR; PG8_SCHED;
;             PG8_LDA(At, 1, 1); PG8_STAGE(PG8_SB(1, 0), b3, voffB); PG8_STAGE(PG8_SB(1, 1), b3 + hstep, voffB); PG8_STAGE(PG8_SA(1, 0), a3, voffA);
;             PG8_WAIT_V(8); PG8_WAIT_L(0); PG8_BAR; PG8_MMA(1, 0, At, B0); PG8_MMA(1, 1, At, B1); PG8_BAR; PG8_SCHED;
	s_setprio 0
	s_add_i32 s63, 0, 0x18000
	s_add_i32 s64, 0, 0x1c000
	ds_read_b128 v[132:135], v240
	ds_read_b128 v[136:139], v240 offset:1024
	ds_read_b128 v[158:161], v240 offset:2048
	ds_read_b128 v[162:165], v240 offset:3072
	ds_read_b128 v[188:191], v241
	ds_read_b128 v[192:195], v241 offset:1024
	ds_read_b128 v[196:199], v241 offset:2048
	ds_read_b128 v[200:203], v241 offset:3072
	s_add_u32 s14, s20, 0x160000
	s_addc_u32 s15, s21, 0
	s_mov_b32 m0, s28
	ds_read_b128 v[204:207], v187 offset:32768
	ds_read_b128 v[208:211], v187 offset:33792
	ds_read_b128 v[212:215], v187 offset:34816
	ds_read_b128 v[216:219], v187 offset:35840
	ds_read_b128 v[220:223], v187 offset:36864
	ds_read_b128 v[224:227], v187 offset:37888
	ds_read_b128 v[228:231], v187 offset:38912
	ds_read_b128 v[232:235], v187 offset:39936
	global_load_lds_dwordx4 v0, s[14:15]
	s_mov_b32 m0, s29
	s_nop 0
	global_load_lds_dwordx4 v150, s[14:15]
	s_waitcnt vmcnt(8)
	s_waitcnt lgkmcnt(0)
	s_setprio 1
	s_barrier
	v_mfma_f32_16x16x32_bf16 v[128:131], v[132:135], v[204:207], v[128:131]
	v_mfma_f32_16x16x32_bf16 v[124:127], v[158:161], v[204:207], v[124:127]
	v_mfma_f32_16x16x32_bf16 v[112:115], v[132:135], v[212:215], v[112:115]
	v_mfma_f32_16x16x32_bf16 v[108:111], v[158:161], v[212:215], v[108:111]
	v_mfma_f32_16x16x32_bf16 v[96:99], v[132:135], v[220:223], v[96:99]
	v_mfma_f32_16x16x32_bf16 v[92:95], v[158:161], v[220:223], v[92:95]
	v_mfma_f32_16x16x32_bf16 v[80:83], v[132:135], v[228:231], v[80:83]
	v_mfma_f32_16x16x32_bf16 v[76:79], v[158:161], v[228:231], v[76:79]
	v_mfma_f32_16x16x32_bf16 v[128:131], v[136:139], v[208:211], v[128:131]
	v_mfma_f32_16x16x32_bf16 v[124:127], v[162:165], v[208:211], v[124:127]
	v_mfma_f32_16x16x32_bf16 v[112:115], v[136:139], v[216:219], v[112:115]
	v_mfma_f32_16x16x32_bf16 v[108:111], v[162:165], v[216:219], v[108:111]
	v_mfma_f32_16x16x32_bf16 v[96:99], v[136:139], v[224:227], v[96:99]
	v_mfma_f32_16x16x32_bf16 v[92:95], v[162:165], v[224:227], v[92:95]
	v_mfma_f32_16x16x32_bf16 v[80:83], v[136:139], v[232:235], v[80:83]
	v_mfma_f32_16x16x32_bf16 v[76:79], v[162:165], v[232:235], v[76:79]
	v_mfma_f32_16x16x32_bf16 v[120:123], v[188:191], v[204:207], v[120:123]
	v_mfma_f32_16x16x32_bf16 v[116:119], v[196:199], v[204:207], v[116:119]
	v_mfma_f32_16x16x32_bf16 v[104:107], v[188:191], v[212:215], v[104:107]
	v_mfma_f32_16x16x32_bf16 v[100:103], v[196:199], v[212:215], v[100:103]
	v_mfma_f32_16x16x32_bf16 v[88:91], v[188:191], v[220:223], v[88:91]
	v_mfma_f32_16x16x32_bf16 v[84:87], v[196:199], v[220:223], v[84:87]
	v_mfma_f32_16x16x32_bf16 v[72:75], v[188:191], v[228:231], v[72:75]
	v_mfma_f32_16x16x32_bf16 v[68:71], v[196:199], v[228:231], v[68:71]
	v_mfma_f32_16x16x32_bf16 v[120:123], v[192:195], v[208:211], v[120:123]
	v_mfma_f32_16x16x32_bf16 v[116:119], v[200:203], v[208:211], v[116:119]
	v_mfma_f32_16x16x32_bf16 v[104:107], v[192:195], v[216:219], v[104:107]
	v_mfma_f32_16x16x32_bf16 v[100:103], v[200:203], v[216:219], v[100:103]
	v_mfma_f32_16x16x32_bf16 v[88:91], v[192:195], v[224:227], v[88:91]
	v_mfma_f32_16x16x32_bf16 v[84:87], v[200:203], v[224:227], v[84:87]
	v_mfma_f32_16x16x32_bf16 v[72:75], v[192:195], v[232:235], v[72:75]
	v_mfma_f32_16x16x32_bf16 v[68:71], v[200:203], v[232:235], v[68:71]
	s_barrier
	s_setprio 0
	s_add_i32 s14, s63, s25
	s_mov_b32 m0, s14
	ds_read_b128 v[204:207], v187 offset:49152
	ds_read_b128 v[208:211], v187 offset:50176
	ds_read_b128 v[212:215], v187 offset:51200
	ds_read_b128 v[216:219], v187 offset:52224
	ds_read_b128 v[220:223], v187 offset:53248
	ds_read_b128 v[224:227], v187 offset:54272
	ds_read_b128 v[228:231], v187 offset:55296
	ds_read_b128 v[232:235], v187 offset:56320
	s_add_u32 vcc_lo, s18, 0x80
	s_addc_u32 vcc_hi, s19, 0
	global_load_lds_dwordx4 v2, vcc
	s_add_i32 m0, s14, 0x2000
	s_add_u32 s14, s18, 0x160080
	v_lshl_add_u64 v[166:167], v[236:237], 0, s[36:37]
	s_addc_u32 s15, s19, 0
	s_add_i32 s18, s64, s25
	global_load_lds_dwordx4 v[166:167], off
	s_mov_b32 m0, s18
	s_nop 0
	global_load_lds_dwordx4 v2, s[14:15]
	v_lshl_add_u64 v[166:167], s[14:15], 0, v[152:153]
	s_add_i32 m0, s18, 0x2000
	s_nop 0
	global_load_lds_dwordx4 v[166:167], off
	s_mov_b32 m0, s30
	s_nop 0
	s_add_u32 vcc_lo, s20, 0x80
	s_addc_u32 vcc_hi, s21, 0
	global_load_lds_dwordx4 v0, vcc
	s_mov_b32 m0, s31
	s_nop 0
	s_add_u32 vcc_lo, s20, 0x80
	s_addc_u32 vcc_hi, s21, 0
	global_load_lds_dwordx4 v150, vcc
	s_waitcnt vmcnt(8)
	s_waitcnt lgkmcnt(0)
	s_setprio 1
	s_barrier
	v_mfma_f32_16x16x32_bf16 v[64:67], v[132:135], v[204:207], v[64:67]
	v_mfma_f32_16x16x32_bf16 v[60:63], v[158:161], v[204:207], v[60:63]
	v_mfma_f32_16x16x32_bf16 v[48:51], v[132:135], v[212:215], v[48:51]
	v_mfma_f32_16x16x32_bf16 v[44:47], v[158:161], v[212:215], v[44:47]
	v_mfma_f32_16x16x32_bf16 v[32:35], v[132:135], v[220:223], v[32:35]
	v_mfma_f32_16x16x32_bf16 v[28:31], v[158:161], v[220:223], v[28:31]
	v_mfma_f32_16x16x32_bf16 v[16:19], v[132:135], v[228:231], v[16:19]
	v_mfma_f32_16x16x32_bf16 v[12:15], v[158:161], v[228:231], v[12:15]
	v_mfma_f32_16x16x32_bf16 v[64:67], v[136:139], v[208:211], v[64:67]
	v_mfma_f32_16x16x32_bf16 v[60:63], v[162:165], v[208:211], v[60:63]
	v_mfma_f32_16x16x32_bf16 v[48:51], v[136:139], v[216:219], v[48:51]
	v_mfma_f32_16x16x32_bf16 v[44:47], v[162:165], v[216:219], v[44:47]
	v_mfma_f32_16x16x32_bf16 v[32:35], v[136:139], v[224:227], v[32:35]
	v_mfma_f32_16x16x32_bf16 v[28:31], v[162:165], v[224:227], v[28:31]
	v_mfma_f32_16x16x32_bf16 v[16:19], v[136:139], v[232:235], v[16:19]
	v_mfma_f32_16x16x32_bf16 v[12:15], v[162:165], v[232:235], v[12:15]
	v_mfma_f32_16x16x32_bf16 v[56:59], v[188:191], v[204:207], v[56:59]
	v_mfma_f32_16x16x32_bf16 v[52:55], v[196:199], v[204:207], v[52:55]
	v_mfma_f32_16x16x32_bf16 v[40:43], v[188:191], v[212:215], v[40:43]
	v_mfma_f32_16x16x32_bf16 v[36:39], v[196:199], v[212:215], v[36:39]
	v_mfma_f32_16x16x32_bf16 v[24:27], v[188:191], v[220:223], v[24:27]
	v_mfma_f32_16x16x32_bf16 v[20:23], v[196:199], v[220:223], v[20:23]
	v_mfma_f32_16x16x32_bf16 v[8:11], v[188:191], v[228:231], v[8:11]
	v_mfma_f32_16x16x32_bf16 v[4:7], v[196:199], v[228:231], v[4:7]
	v_mfma_f32_16x16x32_bf16 v[56:59], v[192:195], v[208:211], v[56:59]
	v_mfma_f32_16x16x32_bf16 v[52:55], v[200:203], v[208:211], v[52:55]
	v_mfma_f32_16x16x32_bf16 v[40:43], v[192:195], v[216:219], v[40:43]
	v_mfma_f32_16x16x32_bf16 v[36:39], v[200:203], v[216:219], v[36:39]
	v_mfma_f32_16x16x32_bf16 v[24:27], v[192:195], v[224:227], v[24:27]
	v_mfma_f32_16x16x32_bf16 v[20:23], v[200:203], v[224:227], v[20:23]
	v_mfma_f32_16x16x32_bf16 v[8:11], v[192:195], v[232:235], v[8:11]
	v_mfma_f32_16x16x32_bf16 v[4:7], v[200:203], v[232:235], v[4:7]
	s_barrier
	s_setprio 0
	s_add_i32 s57, s57, 2
	s_add_u32 s51, s51, 0x100
	s_addc_u32 s56, s56, 0
	s_cmpk_gt_u32 s57, 0x55
	s_mov_b64 s[14:15], s[16:17]

; #define PG8_STAGE(bufoff, gbase, voff) do { _Pragma("unroll") for (int _i = 0; _i < 2; ++_i) \
;         __builtin_amdgcn_global_load_lds((const unsigned*)((const char*)(gbase) + (voff)[_i]), (PG8_LAS unsigned*)(lds + (bufoff) + ldsw + _i * 8192), 16, 0, 0); } while (0)
; #define PG8_LDA(dst, b, h) do { _Pragma("unroll") for (int m = 0; m < 4; ++m) _Pragma("unroll") for (int k = 0; k < 2; ++k) dst[m][k] = *(const PG8_LAS bf16x8*)(lds + PG8_SA(b, h) + aoff + m * 2048 + k * 1024); } while (0)
; #define PG8_LDB(dst, b, h) do { _Pragma("unroll") for (int n = 0; n < 2; ++n) _Pragma("unroll") for (int k = 0; k < 2; ++k) dst[n][k] = *(const PG8_LAS bf16x8*)(lds + PG8_SB(b, h) + boff + n * 2048 + k * 1024); } while (0)
; #define PG8_WAIT_V(n) asm volatile("s_waitcnt vmcnt(" #n ")" ::: "memory")
; #define PG8_WAIT_L(n) asm volatile("s_waitcnt lgkmcnt(" #n ")" ::: "memory")
; #define PG8_BAR __builtin_amdgcn_s_barrier()
; #define PG8_SCHED __builtin_amdgcn_sched_barrier(0)
; template <class Epi, class Sched, bool ALIGN_EPI = false, bool SP2 = false>
; __device__ __forceinline__ void gemm_phase(PG8_LAS unsigned char* lds, const Gemm g, const Sched& S, const Epi& E) {
;     ...
;         const char* nA = has_next ? (const char*)g.A + (size_t)nxt.pm * tstep : cA; const char* nB = has_next ? (const char*)g.Bt + (size_t)nxt.pn * tstep : cB;
;         for (int t = 0; t < nt; t += 2) {
;             const bool last = (t == nt - 2);
;             const char* a1 = cA + (size_t)(t + 1) * kstep;
;             const char* a2 = last ? nA : cA + (size_t)(t + 2) * kstep; const char* b2 = last ? nB : cB + (size_t)(t + 2) * kstep;
;             const char* a3 = a2 + kstep; const char* b3 = b2 + kstep;
;             if (last && has_next) S.a_ready(nxt);
;             if constexpr (SP2) {
;             PG8_LDB(B0, 0, 0); PG8_LDB(B1, 0, 1); PG8_SCHED; PG8_LDA(At, 0, 0); PG8_STAGE(PG8_SA(1, 1), a1 + hstep, voffA);
;             PG8_WAIT_V(8); PG8_WAIT_L(0); PG8_BAR; PG8_MMA(0, 0, At, B0); PG8_MMA(0, 1, At, B1); PG8_BAR; PG8_SCHED;
;             PG8_LDA(At, 0, 1); PG8_STAGE(PG8_SB(0, 0), b2, voffB); PG8_STAGE(PG8_SB(0, 1), b2 + hstep, voffB); PG8_STAGE(PG8_SA(0, 0), a2, voffA);
;             PG8_WAIT_V(8); PG8_WAIT_L(0); PG8_BAR; PG8_MMA(1, 0, At, B0); PG8_MMA(1, 1, At, B1); PG8_BAR; PG8_SCHED;
.LBB0_250:
	s_ashr_i32 s11, s10, 31
	s_lshl_b64 s[12:13], s[10:11], 20
	s_add_u32 s12, s46, s12
	s_addc_u32 s13, s47, s13
	s_and_b64 s[14:15], s[2:3], exec
	s_cselect_b32 s11, s13, s19
	s_cselect_b32 s45, s12, s18
	s_ashr_i32 s7, s6, 31
	s_lshl_b64 s[14:15], s[6:7], 20
	s_add_u32 s14, s25, s14
	s_addc_u32 s15, s26, s15
	s_and_b64 s[22:23], s[2:3], exec
	s_cselect_b32 s7, s15, s21
	s_cselect_b32 s50, s14, s20
	s_add_u32 s18, s18, 0x80080
	s_addc_u32 s19, s19, 0
	s_add_u32 s51, s20, 0x100
	s_addc_u32 s56, s21, 0
	s_mov_b32 s57, -2
	v_add_u32_e32 v166, 0x10000, v156
	v_add_u32_e32 v167, 0x14000, v156
	v_add_u32_e32 v252, 0x18000, v156
	v_add_u32_e32 v253, 0x1c000, v156
	s_add_u32 s20, s18, 0xfff80080
	s_addc_u32 s21, s19, -1
	s_add_i32 s63, 0, 0x10000
	s_cmp_eq_u32 s57, 28
	s_cselect_b32 s23, s11, s21
	s_cselect_b32 s22, s45, s20
	s_cselect_b32 s21, s7, s56
	s_cselect_b32 s20, s50, s51
	s_add_i32 s66, 0, 0x14000
	ds_read_b128 v[184:187], v166
	ds_read_b128 v[188:191], v166 offset:1024
	ds_read_b128 v[192:195], v166 offset:2048
	ds_read_b128 v[196:199], v166 offset:3072
	ds_read_b128 v[200:203], v167
	ds_read_b128 v[204:207], v167 offset:1024
	ds_read_b128 v[208:211], v167 offset:2048
	ds_read_b128 v[212:215], v167 offset:3072
	s_add_i32 m0, s17, 0xc000
	ds_read_b128 v[216:219], v160
	ds_read_b128 v[220:223], v160 offset:1024
	ds_read_b128 v[224:227], v160 offset:2048
	ds_read_b128 v[228:231], v160 offset:3072
	ds_read_b128 v[232:235], v160 offset:4096
	ds_read_b128 v[236:239], v160 offset:5120
	ds_read_b128 v[240:243], v160 offset:6144
	ds_read_b128 v[244:247], v160 offset:7168
	global_load_lds_dwordx4 v136, s[18:19]
	s_add_i32 m0, s17, 0xe000
	s_nop 0
	global_load_lds_dwordx4 v138, s[18:19]
	s_waitcnt vmcnt(32)
	s_waitcnt lgkmcnt(0)
	s_setprio 1
	s_barrier
	v_mfma_f32_16x16x32_bf16 v[128:131], v[184:187], v[216:219], 0
	v_mfma_f32_16x16x32_bf16 v[124:127], v[192:195], v[216:219], 0
	v_mfma_f32_16x16x32_bf16 v[112:115], v[184:187], v[224:227], 0
	v_mfma_f32_16x16x32_bf16 v[108:111], v[192:195], v[224:227], 0
	v_mfma_f32_16x16x32_bf16 v[96:99], v[184:187], v[232:235], 0
	v_mfma_f32_16x16x32_bf16 v[92:95], v[192:195], v[232:235], 0
	v_mfma_f32_16x16x32_bf16 v[80:83], v[184:187], v[240:243], 0
	v_mfma_f32_16x16x32_bf16 v[76:79], v[192:195], v[240:243], 0
	v_mfma_f32_16x16x32_bf16 v[128:131], v[188:191], v[220:223], v[128:131]
	v_mfma_f32_16x16x32_bf16 v[124:127], v[196:199], v[220:223], v[124:127]
	v_mfma_f32_16x16x32_bf16 v[112:115], v[188:191], v[228:231], v[112:115]
	v_mfma_f32_16x16x32_bf16 v[108:111], v[196:199], v[228:231], v[108:111]
	v_mfma_f32_16x16x32_bf16 v[96:99], v[188:191], v[236:239], v[96:99]
	v_mfma_f32_16x16x32_bf16 v[92:95], v[196:199], v[236:239], v[92:95]
	v_mfma_f32_16x16x32_bf16 v[80:83], v[188:191], v[244:247], v[80:83]
	v_mfma_f32_16x16x32_bf16 v[76:79], v[196:199], v[244:247], v[76:79]
	v_mfma_f32_16x16x32_bf16 v[120:123], v[200:203], v[216:219], 0
	v_mfma_f32_16x16x32_bf16 v[116:119], v[208:211], v[216:219], 0
	v_mfma_f32_16x16x32_bf16 v[104:107], v[200:203], v[224:227], 0
	v_mfma_f32_16x16x32_bf16 v[100:103], v[208:211], v[224:227], 0
	v_mfma_f32_16x16x32_bf16 v[88:91], v[200:203], v[232:235], 0
	v_mfma_f32_16x16x32_bf16 v[84:87], v[208:211], v[232:235], 0
	v_mfma_f32_16x16x32_bf16 v[72:75], v[200:203], v[240:243], 0
	v_mfma_f32_16x16x32_bf16 v[68:71], v[208:211], v[240:243], 0
	v_mfma_f32_16x16x32_bf16 v[120:123], v[204:207], v[220:223], v[120:123]
	v_mfma_f32_16x16x32_bf16 v[116:119], v[212:215], v[220:223], v[116:119]
	v_mfma_f32_16x16x32_bf16 v[104:107], v[204:207], v[228:231], v[104:107]
	v_mfma_f32_16x16x32_bf16 v[100:103], v[212:215], v[228:231], v[100:103]
	v_mfma_f32_16x16x32_bf16 v[88:91], v[204:207], v[236:239], v[88:91]
	v_mfma_f32_16x16x32_bf16 v[84:87], v[212:215], v[236:239], v[84:87]
	v_mfma_f32_16x16x32_bf16 v[72:75], v[204:207], v[244:247], v[72:75]
	v_mfma_f32_16x16x32_bf16 v[68:71], v[212:215], v[244:247], v[68:71]
	s_barrier
	s_setprio 0
	s_add_i32 s63, s63, s27
	s_mov_b32 m0, s63
	ds_read_b128 v[216:219], v160 offset:16384
	ds_read_b128 v[220:223], v160 offset:17408
	ds_read_b128 v[224:227], v160 offset:18432
	ds_read_b128 v[228:231], v160 offset:19456
	ds_read_b128 v[232:235], v160 offset:20480
	ds_read_b128 v[236:239], v160 offset:21504
	ds_read_b128 v[240:243], v160 offset:22528
	ds_read_b128 v[244:247], v160 offset:23552
	global_load_lds_dwordx4 v2, s[20:21]
	s_add_i32 m0, s63, 0x2000
	s_add_u32 s64, s20, 0x80000
	s_addc_u32 s65, s21, 0
	s_add_i32 s63, s66, s27
	global_load_lds_dwordx4 v0, s[20:21]
	s_mov_b32 m0, s63
	v_lshl_add_u64 v[250:251], s[22:23], 0, v[132:133]
	global_load_lds_dwordx4 v2, s[64:65]
	s_add_i32 m0, s63, 0x2000
	s_nop 0
	global_load_lds_dwordx4 v0, s[64:65]
	v_lshl_add_u64 v[248:249], s[22:23], 0, v[134:135]
	s_mov_b32 m0, s17
	s_nop 0
	global_load_lds_dwordx4 v[248:249], off
	s_mov_b32 m0, s29
	s_nop 0
	global_load_lds_dwordx4 v[250:251], off
	s_waitcnt vmcnt(8)
	s_waitcnt lgkmcnt(0)
	s_setprio 1
	s_barrier
; #define PG8_STAGE(bufoff, gbase, voff) do { _Pragma("unroll") for (int _i = 0; _i < 2; ++_i) \
;         __builtin_amdgcn_global_load_lds((const unsigned*)((const char*)(gbase) + (voff)[_i]), (PG8_LAS unsigned*)(lds + (bufoff) + ldsw + _i * 8192), 16, 0, 0); } while (0)
; #define PG8_LDA(dst, b, h) do { _Pragma("unroll") for (int m = 0; m < 4; ++m) _Pragma("unroll") for (int k = 0; k < 2; ++k) dst[m][k] = *(const PG8_LAS bf16x8*)(lds + PG8_SA(b, h) + aoff + m * 2048 + k * 1024); } while (0)
; #define PG8_LDB(dst, b, h) do { _Pragma("unroll") for (int n = 0; n < 2; ++n) _Pragma("unroll") for (int k = 0; k < 2; ++k) dst[n][k] = *(const PG8_LAS bf16x8*)(lds + PG8_SB(b, h) + boff + n * 2048 + k * 1024); } while (0)
; #define PG8_MMA(ai, bj, At, Bt) do { __builtin_amdgcn_s_setprio(1); _Pragma("unroll") for (int m = 0; m < 4; ++m) _Pragma("unroll") for (int n = 0; n < 2; ++n) _Pragma("unroll") for (int k = 0; k < 2; ++k) \
;         acc[ai][bj][m][n] = __builtin_amdgcn_mfma_f32_16x16x32_bf16(Bt[n][k], At[m][k], acc[ai][bj][m][n], 0, 0, 0); __builtin_amdgcn_s_setprio(0); } while (0)
; #define PG8_WAIT_V(n) asm volatile("s_waitcnt vmcnt(" #n ")" ::: "memory")
; #define PG8_WAIT_L(n) asm volatile("s_waitcnt lgkmcnt(" #n ")" ::: "memory")
; #define PG8_BAR __builtin_amdgcn_s_barrier()
; #define PG8_SCHED __builtin_amdgcn_sched_barrier(0)
; template <class Epi, class Sched, bool ALIGN_EPI = false, bool SP2 = false>
; __device__ __forceinline__ void gemm_phase(PG8_LAS unsigned char* lds, const Gemm g, const Sched& S, const Epi& E) {
;     ...
;             PG8_WAIT_V(8); PG8_WAIT_L(0); PG8_BAR; PG8_MMA(1, 0, At, B0); PG8_MMA(1, 1, At, B1); PG8_BAR; PG8_SCHED;
;             PG8_LDB(B0, 1, 0); PG8_LDB(B1, 1, 1); PG8_SCHED; PG8_LDA(At, 1, 0); PG8_STAGE(PG8_SA(0, 1), a2 + hstep, voffA);
;             PG8_WAIT_V(8); PG8_WAIT_L(0); PG8_BAR; PG8_MMA(0, 0, At, B0); PG8_MMA(0, 1, At, B1); PG8_BAR; PG8_SCHED;
	v_mfma_f32_16x16x32_bf16 v[64:67], v[184:187], v[216:219], 0
	v_mfma_f32_16x16x32_bf16 v[60:63], v[192:195], v[216:219], 0
	v_mfma_f32_16x16x32_bf16 v[48:51], v[184:187], v[224:227], 0
	v_mfma_f32_16x16x32_bf16 v[44:47], v[192:195], v[224:227], 0
	v_mfma_f32_16x16x32_bf16 v[32:35], v[184:187], v[232:235], 0
	v_mfma_f32_16x16x32_bf16 v[28:31], v[192:195], v[232:235], 0
	v_mfma_f32_16x16x32_bf16 v[16:19], v[184:187], v[240:243], 0
	v_mfma_f32_16x16x32_bf16 v[12:15], v[192:195], v[240:243], 0
	v_mfma_f32_16x16x32_bf16 v[64:67], v[188:191], v[220:223], v[64:67]
	v_mfma_f32_16x16x32_bf16 v[60:63], v[196:199], v[220:223], v[60:63]
	v_mfma_f32_16x16x32_bf16 v[48:51], v[188:191], v[228:231], v[48:51]
	v_mfma_f32_16x16x32_bf16 v[44:47], v[196:199], v[228:231], v[44:47]
	v_mfma_f32_16x16x32_bf16 v[32:35], v[188:191], v[236:239], v[32:35]
	v_mfma_f32_16x16x32_bf16 v[28:31], v[196:199], v[236:239], v[28:31]
	v_mfma_f32_16x16x32_bf16 v[16:19], v[188:191], v[244:247], v[16:19]
	v_mfma_f32_16x16x32_bf16 v[12:15], v[196:199], v[244:247], v[12:15]
	v_mfma_f32_16x16x32_bf16 v[56:59], v[200:203], v[216:219], 0
	v_mfma_f32_16x16x32_bf16 v[52:55], v[208:211], v[216:219], 0
	v_mfma_f32_16x16x32_bf16 v[40:43], v[200:203], v[224:227], 0
	v_mfma_f32_16x16x32_bf16 v[36:39], v[208:211], v[224:227], 0
	v_mfma_f32_16x16x32_bf16 v[24:27], v[200:203], v[232:235], 0
	v_mfma_f32_16x16x32_bf16 v[20:23], v[208:211], v[232:235], 0
	v_mfma_f32_16x16x32_bf16 v[8:11], v[200:203], v[240:243], 0
	v_mfma_f32_16x16x32_bf16 v[4:7], v[208:211], v[240:243], 0
	v_mfma_f32_16x16x32_bf16 v[56:59], v[204:207], v[220:223], v[56:59]
	v_mfma_f32_16x16x32_bf16 v[52:55], v[212:215], v[220:223], v[52:55]
	v_mfma_f32_16x16x32_bf16 v[40:43], v[204:207], v[228:231], v[40:43]
	v_mfma_f32_16x16x32_bf16 v[36:39], v[212:215], v[228:231], v[36:39]
	v_mfma_f32_16x16x32_bf16 v[24:27], v[204:207], v[236:239], v[24:27]
	v_mfma_f32_16x16x32_bf16 v[20:23], v[212:215], v[236:239], v[20:23]
	v_mfma_f32_16x16x32_bf16 v[8:11], v[204:207], v[244:247], v[8:11]
	v_mfma_f32_16x16x32_bf16 v[4:7], v[212:215], v[244:247], v[4:7]
	s_barrier
	s_setprio 0
	s_add_i32 s63, 0, 0x18000
	s_add_i32 s64, 0, 0x1c000
	ds_read_b128 v[184:187], v252
	ds_read_b128 v[188:191], v252 offset:1024
	ds_read_b128 v[192:195], v252 offset:2048
	ds_read_b128 v[196:199], v252 offset:3072
	ds_read_b128 v[200:203], v253
	ds_read_b128 v[204:207], v253 offset:1024
	ds_read_b128 v[208:211], v253 offset:2048
	ds_read_b128 v[212:215], v253 offset:3072
	s_add_u32 s22, s22, 0x80000
	s_addc_u32 s23, s23, 0
	s_mov_b32 m0, s30
	ds_read_b128 v[216:219], v160 offset:32768
	ds_read_b128 v[220:223], v160 offset:33792
	ds_read_b128 v[224:227], v160 offset:34816
	ds_read_b128 v[228:231], v160 offset:35840
	ds_read_b128 v[232:235], v160 offset:36864
	ds_read_b128 v[236:239], v160 offset:37888
	ds_read_b128 v[240:243], v160 offset:38912
	ds_read_b128 v[244:247], v160 offset:39936
	global_load_lds_dwordx4 v134, s[22:23]
	s_mov_b32 m0, s31
	s_nop 0
	global_load_lds_dwordx4 v132, s[22:23]
	s_waitcnt vmcnt(8)
	s_waitcnt lgkmcnt(0)
	s_setprio 1
	s_barrier
	v_mfma_f32_16x16x32_bf16 v[128:131], v[184:187], v[216:219], v[128:131]
	v_mfma_f32_16x16x32_bf16 v[124:127], v[192:195], v[216:219], v[124:127]
	v_mfma_f32_16x16x32_bf16 v[112:115], v[184:187], v[224:227], v[112:115]
	v_mfma_f32_16x16x32_bf16 v[108:111], v[192:195], v[224:227], v[108:111]
	v_mfma_f32_16x16x32_bf16 v[96:99], v[184:187], v[232:235], v[96:99]
	v_mfma_f32_16x16x32_bf16 v[92:95], v[192:195], v[232:235], v[92:95]
	v_mfma_f32_16x16x32_bf16 v[80:83], v[184:187], v[240:243], v[80:83]
	v_mfma_f32_16x16x32_bf16 v[76:79], v[192:195], v[240:243], v[76:79]
	v_mfma_f32_16x16x32_bf16 v[128:131], v[188:191], v[220:223], v[128:131]
	v_mfma_f32_16x16x32_bf16 v[124:127], v[196:199], v[220:223], v[124:127]
	v_mfma_f32_16x16x32_bf16 v[112:115], v[188:191], v[228:231], v[112:115]
	v_mfma_f32_16x16x32_bf16 v[108:111], v[196:199], v[228:231], v[108:111]
	v_mfma_f32_16x16x32_bf16 v[96:99], v[188:191], v[236:239], v[96:99]
	v_mfma_f32_16x16x32_bf16 v[92:95], v[196:199], v[236:239], v[92:95]
	v_mfma_f32_16x16x32_bf16 v[80:83], v[188:191], v[244:247], v[80:83]
	v_mfma_f32_16x16x32_bf16 v[76:79], v[196:199], v[244:247], v[76:79]
	v_mfma_f32_16x16x32_bf16 v[120:123], v[200:203], v[216:219], v[120:123]
	v_mfma_f32_16x16x32_bf16 v[116:119], v[208:211], v[216:219], v[116:119]
	v_mfma_f32_16x16x32_bf16 v[104:107], v[200:203], v[224:227], v[104:107]
	v_mfma_f32_16x16x32_bf16 v[100:103], v[208:211], v[224:227], v[100:103]
	v_mfma_f32_16x16x32_bf16 v[88:91], v[200:203], v[232:235], v[88:91]
	v_mfma_f32_16x16x32_bf16 v[84:87], v[208:211], v[232:235], v[84:87]
	v_mfma_f32_16x16x32_bf16 v[72:75], v[200:203], v[240:243], v[72:75]
	v_mfma_f32_16x16x32_bf16 v[68:71], v[208:211], v[240:243], v[68:71]
	v_mfma_f32_16x16x32_bf16 v[120:123], v[204:207], v[220:223], v[120:123]
	v_mfma_f32_16x16x32_bf16 v[116:119], v[212:215], v[220:223], v[116:119]
	v_mfma_f32_16x16x32_bf16 v[104:107], v[204:207], v[228:231], v[104:107]
	v_mfma_f32_16x16x32_bf16 v[100:103], v[212:215], v[228:231], v[100:103]
	v_mfma_f32_16x16x32_bf16 v[88:91], v[204:207], v[236:239], v[88:91]
	v_mfma_f32_16x16x32_bf16 v[84:87], v[212:215], v[236:239], v[84:87]
	v_mfma_f32_16x16x32_bf16 v[72:75], v[204:207], v[244:247], v[72:75]
	v_mfma_f32_16x16x32_bf16 v[68:71], v[212:215], v[244:247], v[68:71]
	s_barrier
; #define PG8_STAGE(bufoff, gbase, voff) do { _Pragma("unroll") for (int _i = 0; _i < 2; ++_i) \
;         __builtin_amdgcn_global_load_lds((const unsigned*)((const char*)(gbase) + (voff)[_i]), (PG8_LAS unsigned*)(lds + (bufoff) + ldsw + _i * 8192), 16, 0, 0); } while (0)
; #define PG8_LDA(dst, b, h) do { _Pragma("unroll") for (int m = 0; m < 4; ++m) _Pragma("unroll") for (int k = 0; k < 2; ++k) dst[m][k] = *(const PG8_LAS bf16x8*)(lds + PG8_SA(b, h) + aoff + m * 2048 + k * 1024); } while (0)
; #define PG8_MMA(ai, bj, At, Bt) do { __builtin_amdgcn_s_setprio(1); _Pragma("unroll") for (int m = 0; m < 4; ++m) _Pragma("unroll") for (int n = 0; n < 2; ++n) _Pragma("unroll") for (int k = 0; k < 2; ++k) \
;         acc[ai][bj][m][n] = __builtin_amdgcn_mfma_f32_16x16x32_bf16(Bt[n][k], At[m][k], acc[ai][bj][m][n], 0, 0, 0); __builtin_amdgcn_s_setprio(0); } while (0)
; #define PG8_WAIT_V(n) asm volatile("s_waitcnt vmcnt(" #n ")" ::: "memory")
; #define PG8_WAIT_L(n) asm volatile("s_waitcnt lgkmcnt(" #n ")" ::: "memory")
; #define PG8_BAR __builtin_amdgcn_s_barrier()
; #define PG8_SCHED __builtin_amdgcn_sched_barrier(0)
; template <class Epi, class Sched, bool ALIGN_EPI = false, bool SP2 = false>
; __device__ __forceinline__ void gemm_phase(PG8_LAS unsigned char* lds, const Gemm g, const Sched& S, const Epi& E) {
;     ...
;             PG8_LDA(At, 1, 1); PG8_STAGE(PG8_SB(1, 0), b3, voffB); PG8_STAGE(PG8_SB(1, 1), b3 + hstep, voffB); PG8_STAGE(PG8_SA(1, 0), a3, voffA);
;             PG8_WAIT_V(8); PG8_WAIT_L(0); PG8_BAR; PG8_MMA(1, 0, At, B0); PG8_MMA(1, 1, At, B1); PG8_BAR; PG8_SCHED;
	s_setprio 0
	s_add_i32 s22, s63, s27
	s_mov_b32 m0, s22
	ds_read_b128 v[216:219], v160 offset:49152
	ds_read_b128 v[220:223], v160 offset:50176
	ds_read_b128 v[224:227], v160 offset:51200
	ds_read_b128 v[228:231], v160 offset:52224
	ds_read_b128 v[232:235], v160 offset:53248
	ds_read_b128 v[236:239], v160 offset:54272
	ds_read_b128 v[240:243], v160 offset:55296
	ds_read_b128 v[244:247], v160 offset:56320
	s_add_u32 vcc_lo, s20, 0x80
	s_addc_u32 vcc_hi, s21, 0
	global_load_lds_dwordx4 v2, vcc
	s_add_i32 m0, s22, 0x2000
	s_add_u32 s20, s20, 0x80080
	s_addc_u32 s21, s21, 0
	s_add_i32 s22, s64, s27
	s_add_u32 vcc_lo, s20, 0xfff80000
	s_addc_u32 vcc_hi, s21, -1
	global_load_lds_dwordx4 v0, vcc
	s_mov_b32 m0, s22
	s_nop 0
	global_load_lds_dwordx4 v2, s[20:21]
	s_add_i32 m0, s22, 0x2000
	s_nop 0
	global_load_lds_dwordx4 v0, s[20:21]
	v_lshl_add_u64 v[152:153], v[248:249], 0, s[36:37]
	s_mov_b32 m0, s34
	s_nop 0
	global_load_lds_dwordx4 v[152:153], off
	v_lshl_add_u64 v[152:153], v[250:251], 0, s[36:37]
	s_mov_b32 m0, s35
	s_nop 0
	global_load_lds_dwordx4 v[152:153], off
	s_waitcnt vmcnt(8)
	s_waitcnt lgkmcnt(0)
	s_setprio 1
	s_barrier
	v_mfma_f32_16x16x32_bf16 v[64:67], v[184:187], v[216:219], v[64:67]
	v_mfma_f32_16x16x32_bf16 v[60:63], v[192:195], v[216:219], v[60:63]
	v_mfma_f32_16x16x32_bf16 v[48:51], v[184:187], v[224:227], v[48:51]
	v_mfma_f32_16x16x32_bf16 v[44:47], v[192:195], v[224:227], v[44:47]
	v_mfma_f32_16x16x32_bf16 v[32:35], v[184:187], v[232:235], v[32:35]
	v_mfma_f32_16x16x32_bf16 v[28:31], v[192:195], v[232:235], v[28:31]
	v_mfma_f32_16x16x32_bf16 v[16:19], v[184:187], v[240:243], v[16:19]
	v_mfma_f32_16x16x32_bf16 v[12:15], v[192:195], v[240:243], v[12:15]
	v_mfma_f32_16x16x32_bf16 v[64:67], v[188:191], v[220:223], v[64:67]
	v_mfma_f32_16x16x32_bf16 v[60:63], v[196:199], v[220:223], v[60:63]
	v_mfma_f32_16x16x32_bf16 v[48:51], v[188:191], v[228:231], v[48:51]
	v_mfma_f32_16x16x32_bf16 v[44:47], v[196:199], v[228:231], v[44:47]
	v_mfma_f32_16x16x32_bf16 v[32:35], v[188:191], v[236:239], v[32:35]
	v_mfma_f32_16x16x32_bf16 v[28:31], v[196:199], v[236:239], v[28:31]
	v_mfma_f32_16x16x32_bf16 v[16:19], v[188:191], v[244:247], v[16:19]
	v_mfma_f32_16x16x32_bf16 v[12:15], v[196:199], v[244:247], v[12:15]
	v_mfma_f32_16x16x32_bf16 v[56:59], v[200:203], v[216:219], v[56:59]
	v_mfma_f32_16x16x32_bf16 v[52:55], v[208:211], v[216:219], v[52:55]
	v_mfma_f32_16x16x32_bf16 v[40:43], v[200:203], v[224:227], v[40:43]
	v_mfma_f32_16x16x32_bf16 v[36:39], v[208:211], v[224:227], v[36:39]
	v_mfma_f32_16x16x32_bf16 v[24:27], v[200:203], v[232:235], v[24:27]
	v_mfma_f32_16x16x32_bf16 v[20:23], v[208:211], v[232:235], v[20:23]
	v_mfma_f32_16x16x32_bf16 v[8:11], v[200:203], v[240:243], v[8:11]
	v_mfma_f32_16x16x32_bf16 v[4:7], v[208:211], v[240:243], v[4:7]
	v_mfma_f32_16x16x32_bf16 v[56:59], v[204:207], v[220:223], v[56:59]
	v_mfma_f32_16x16x32_bf16 v[52:55], v[212:215], v[220:223], v[52:55]
	v_mfma_f32_16x16x32_bf16 v[40:43], v[204:207], v[228:231], v[40:43]
	v_mfma_f32_16x16x32_bf16 v[36:39], v[212:215], v[228:231], v[36:39]
	v_mfma_f32_16x16x32_bf16 v[24:27], v[204:207], v[236:239], v[24:27]
	v_mfma_f32_16x16x32_bf16 v[20:23], v[212:215], v[236:239], v[20:23]
	v_mfma_f32_16x16x32_bf16 v[8:11], v[204:207], v[244:247], v[8:11]
	v_mfma_f32_16x16x32_bf16 v[4:7], v[212:215], v[244:247], v[4:7]
	s_barrier
	s_setprio 0
	s_add_i32 s57, s57, 2
	s_add_u32 s18, s18, 0x100
	s_addc_u32 s19, s19, 0
	s_add_u32 s51, s51, 0x100
	s_addc_u32 s56, s56, 0
	s_cmp_gt_u32 s57, 29

; #define PG8_STAGE(bufoff, gbase, voff) do { _Pragma("unroll") for (int _i = 0; _i < 2; ++_i) \
;         __builtin_amdgcn_global_load_lds((const unsigned*)((const char*)(gbase) + (voff)[_i]), (PG8_LAS unsigned*)(lds + (bufoff) + ldsw + _i * 8192), 16, 0, 0); } while (0)
; #define PG8_LDA(dst, b, h) do { _Pragma("unroll") for (int m = 0; m < 4; ++m) _Pragma("unroll") for (int k = 0; k < 2; ++k) dst[m][k] = *(const PG8_LAS bf16x8*)(lds + PG8_SA(b, h) + aoff + m * 2048 + k * 1024); } while (0)
; #define PG8_LDB(dst, b, h) do { _Pragma("unroll") for (int n = 0; n < 2; ++n) _Pragma("unroll") for (int k = 0; k < 2; ++k) dst[n][k] = *(const PG8_LAS bf16x8*)(lds + PG8_SB(b, h) + boff + n * 2048 + k * 1024); } while (0)
; #define PG8_WAIT_V(n) asm volatile("s_waitcnt vmcnt(" #n ")" ::: "memory")
; #define PG8_WAIT_L(n) asm volatile("s_waitcnt lgkmcnt(" #n ")" ::: "memory")
; #define PG8_BAR __builtin_amdgcn_s_barrier()
; #define PG8_SCHED __builtin_amdgcn_sched_barrier(0)
; template <class Epi, class Sched, bool ALIGN_EPI = false, bool SP2 = false>
; __device__ __forceinline__ void gemm_phase(PG8_LAS unsigned char* lds, const Gemm g, const Sched& S, const Epi& E) {
;     ...
;         const char* nA = has_next ? (const char*)g.A + (size_t)nxt.pm * tstep : cA; const char* nB = has_next ? (const char*)g.Bt + (size_t)nxt.pn * tstep : cB;
;         for (int t = 0; t < nt; t += 2) {
;             const bool last = (t == nt - 2);
;             const char* a1 = cA + (size_t)(t + 1) * kstep;
;             const char* a2 = last ? nA : cA + (size_t)(t + 2) * kstep; const char* b2 = last ? nB : cB + (size_t)(t + 2) * kstep;
;             const char* a3 = a2 + kstep; const char* b3 = b2 + kstep;
;             if (last && has_next) S.a_ready(nxt);
;             if constexpr (SP2) {
;             PG8_LDB(B0, 0, 0); PG8_LDB(B1, 0, 1); PG8_SCHED; PG8_LDA(At, 0, 0); PG8_STAGE(PG8_SA(1, 1), a1 + hstep, voffA);
;             PG8_WAIT_V(8); PG8_WAIT_L(0); PG8_BAR; PG8_MMA(0, 0, At, B0); PG8_MMA(0, 1, At, B1); PG8_BAR; PG8_SCHED;
;             PG8_LDA(At, 0, 1); PG8_STAGE(PG8_SB(0, 0), b2, voffB); PG8_STAGE(PG8_SB(0, 1), b2 + hstep, voffB); PG8_STAGE(PG8_SA(0, 0), a2, voffA);
;             PG8_WAIT_V(8); PG8_WAIT_L(0); PG8_BAR; PG8_MMA(1, 0, At, B0); PG8_MMA(1, 1, At, B1); PG8_BAR; PG8_SCHED;
.LBB0_482:
	s_ashr_i32 s13, s12, 31
	s_lshl_b64 s[14:15], s[12:13], 20
	s_add_u32 s14, s54, s14
	s_addc_u32 s15, s55, s15
	s_and_b64 s[16:17], s[4:5], exec
	s_cselect_b32 s13, s15, s23
	s_cselect_b32 s19, s14, s22
	s_ashr_i32 s11, s10, 31
	s_lshl_b64 s[16:17], s[10:11], 20
	s_add_u32 s16, s29, s16
	s_addc_u32 s17, s30, s17
	s_and_b64 s[26:27], s[4:5], exec
	s_cselect_b32 s11, s17, s25
	s_cselect_b32 s56, s16, s24
	s_add_u32 s22, s22, 0x80080
	s_addc_u32 s23, s23, 0
	s_add_u32 s57, s24, 0x100
	s_addc_u32 s63, s25, 0
	s_mov_b32 s64, -2
	s_waitcnt lgkmcnt(0)
	v_add_u32_e32 v236, 0x10000, v185
	v_add_u32_e32 v237, 0x14000, v185
	v_add_u32_e32 v242, 0x18000, v185
	v_add_u32_e32 v243, 0x1c000, v185
	s_add_u32 s24, s22, 0xfff80080
	s_addc_u32 s25, s23, -1
	s_add_i32 s65, 0, 0x10000
	s_cmp_eq_u32 s64, 28
	s_cselect_b32 s27, s13, s25
	s_cselect_b32 s26, s19, s24
	s_cselect_b32 s25, s11, s63
	s_cselect_b32 s24, s56, s57
	s_add_i32 s76, 0, 0x14000
	ds_read_b128 v[132:135], v236
	ds_read_b128 v[136:139], v236 offset:1024
	ds_read_b128 v[158:161], v236 offset:2048
	ds_read_b128 v[162:165], v236 offset:3072
	ds_read_b128 v[188:191], v237
	ds_read_b128 v[192:195], v237 offset:1024
	ds_read_b128 v[196:199], v237 offset:2048
	ds_read_b128 v[200:203], v237 offset:3072
	s_add_i32 m0, s21, 0xc000
	ds_read_b128 v[204:207], v187
	ds_read_b128 v[208:211], v187 offset:1024
	ds_read_b128 v[212:215], v187 offset:2048
	ds_read_b128 v[216:219], v187 offset:3072
	ds_read_b128 v[220:223], v187 offset:4096
	ds_read_b128 v[224:227], v187 offset:5120
	ds_read_b128 v[228:231], v187 offset:6144
	ds_read_b128 v[232:235], v187 offset:7168
	global_load_lds_dwordx4 v154, s[22:23]
	s_add_i32 m0, s21, 0xe000
	s_nop 0
	global_load_lds_dwordx4 v156, s[22:23]
	s_waitcnt vmcnt(24)
	s_waitcnt lgkmcnt(0)
	s_setprio 1
	s_barrier
	v_mfma_f32_16x16x32_bf16 v[128:131], v[132:135], v[204:207], 0
	v_mfma_f32_16x16x32_bf16 v[124:127], v[158:161], v[204:207], 0
	v_mfma_f32_16x16x32_bf16 v[112:115], v[132:135], v[212:215], 0
	v_mfma_f32_16x16x32_bf16 v[108:111], v[158:161], v[212:215], 0
	v_mfma_f32_16x16x32_bf16 v[96:99], v[132:135], v[220:223], 0
	v_mfma_f32_16x16x32_bf16 v[92:95], v[158:161], v[220:223], 0
	v_mfma_f32_16x16x32_bf16 v[80:83], v[132:135], v[228:231], 0
	v_mfma_f32_16x16x32_bf16 v[76:79], v[158:161], v[228:231], 0
	v_mfma_f32_16x16x32_bf16 v[128:131], v[136:139], v[208:211], v[128:131]
	v_mfma_f32_16x16x32_bf16 v[124:127], v[162:165], v[208:211], v[124:127]
	v_mfma_f32_16x16x32_bf16 v[112:115], v[136:139], v[216:219], v[112:115]
	v_mfma_f32_16x16x32_bf16 v[108:111], v[162:165], v[216:219], v[108:111]
	v_mfma_f32_16x16x32_bf16 v[96:99], v[136:139], v[224:227], v[96:99]
	v_mfma_f32_16x16x32_bf16 v[92:95], v[162:165], v[224:227], v[92:95]
	v_mfma_f32_16x16x32_bf16 v[80:83], v[136:139], v[232:235], v[80:83]
	v_mfma_f32_16x16x32_bf16 v[76:79], v[162:165], v[232:235], v[76:79]
	v_mfma_f32_16x16x32_bf16 v[120:123], v[188:191], v[204:207], 0
	v_mfma_f32_16x16x32_bf16 v[116:119], v[196:199], v[204:207], 0
	v_mfma_f32_16x16x32_bf16 v[104:107], v[188:191], v[212:215], 0
	v_mfma_f32_16x16x32_bf16 v[100:103], v[196:199], v[212:215], 0
	v_mfma_f32_16x16x32_bf16 v[88:91], v[188:191], v[220:223], 0
	v_mfma_f32_16x16x32_bf16 v[84:87], v[196:199], v[220:223], 0
	v_mfma_f32_16x16x32_bf16 v[72:75], v[188:191], v[228:231], 0
	v_mfma_f32_16x16x32_bf16 v[68:71], v[196:199], v[228:231], 0
	v_mfma_f32_16x16x32_bf16 v[120:123], v[192:195], v[208:211], v[120:123]
	v_mfma_f32_16x16x32_bf16 v[116:119], v[200:203], v[208:211], v[116:119]
	v_mfma_f32_16x16x32_bf16 v[104:107], v[192:195], v[216:219], v[104:107]
	v_mfma_f32_16x16x32_bf16 v[100:103], v[200:203], v[216:219], v[100:103]
	v_mfma_f32_16x16x32_bf16 v[88:91], v[192:195], v[224:227], v[88:91]
	v_mfma_f32_16x16x32_bf16 v[84:87], v[200:203], v[224:227], v[84:87]
	v_mfma_f32_16x16x32_bf16 v[72:75], v[192:195], v[232:235], v[72:75]
	v_mfma_f32_16x16x32_bf16 v[68:71], v[200:203], v[232:235], v[68:71]
	s_barrier
	s_setprio 0
	s_add_i32 s65, s65, s31
	s_mov_b32 m0, s65
	ds_read_b128 v[204:207], v187 offset:16384
	ds_read_b128 v[208:211], v187 offset:17408
	ds_read_b128 v[212:215], v187 offset:18432
	ds_read_b128 v[216:219], v187 offset:19456
	ds_read_b128 v[220:223], v187 offset:20480
	ds_read_b128 v[224:227], v187 offset:21504
	ds_read_b128 v[228:231], v187 offset:22528
	ds_read_b128 v[232:235], v187 offset:23552
	global_load_lds_dwordx4 v2, s[24:25]
	s_add_i32 m0, s65, 0x2000
	s_add_u32 s66, s24, 0x80000
	s_addc_u32 s67, s25, 0
	s_add_i32 s65, s76, s31
	global_load_lds_dwordx4 v152, s[24:25]
	s_mov_b32 m0, s65
	v_lshl_add_u64 v[240:241], s[26:27], 0, v[150:151]
	global_load_lds_dwordx4 v2, s[66:67]
	s_add_i32 m0, s65, 0x2000
	s_nop 0
	global_load_lds_dwordx4 v152, s[66:67]
	v_lshl_add_u64 v[238:239], s[26:27], 0, v[0:1]
	s_mov_b32 m0, s21
	s_nop 0
	global_load_lds_dwordx4 v[238:239], off
	s_mov_b32 m0, s34
	s_nop 0
	global_load_lds_dwordx4 v[240:241], off
	s_waitcnt vmcnt(8)
	s_waitcnt lgkmcnt(0)
	s_setprio 1
	s_barrier
; #define PG8_STAGE(bufoff, gbase, voff) do { _Pragma("unroll") for (int _i = 0; _i < 2; ++_i) \
;         __builtin_amdgcn_global_load_lds((const unsigned*)((const char*)(gbase) + (voff)[_i]), (PG8_LAS unsigned*)(lds + (bufoff) + ldsw + _i * 8192), 16, 0, 0); } while (0)
; #define PG8_LDA(dst, b, h) do { _Pragma("unroll") for (int m = 0; m < 4; ++m) _Pragma("unroll") for (int k = 0; k < 2; ++k) dst[m][k] = *(const PG8_LAS bf16x8*)(lds + PG8_SA(b, h) + aoff + m * 2048 + k * 1024); } while (0)
; #define PG8_LDB(dst, b, h) do { _Pragma("unroll") for (int n = 0; n < 2; ++n) _Pragma("unroll") for (int k = 0; k < 2; ++k) dst[n][k] = *(const PG8_LAS bf16x8*)(lds + PG8_SB(b, h) + boff + n * 2048 + k * 1024); } while (0)
; #define PG8_MMA(ai, bj, At, Bt) do { __builtin_amdgcn_s_setprio(1); _Pragma("unroll") for (int m = 0; m < 4; ++m) _Pragma("unroll") for (int n = 0; n < 2; ++n) _Pragma("unroll") for (int k = 0; k < 2; ++k) \
;         acc[ai][bj][m][n] = __builtin_amdgcn_mfma_f32_16x16x32_bf16(Bt[n][k], At[m][k], acc[ai][bj][m][n], 0, 0, 0); __builtin_amdgcn_s_setprio(0); } while (0)
; #define PG8_WAIT_V(n) asm volatile("s_waitcnt vmcnt(" #n ")" ::: "memory")
; #define PG8_WAIT_L(n) asm volatile("s_waitcnt lgkmcnt(" #n ")" ::: "memory")
; #define PG8_BAR __builtin_amdgcn_s_barrier()
; #define PG8_SCHED __builtin_amdgcn_sched_barrier(0)
; template <class Epi, class Sched, bool ALIGN_EPI = false, bool SP2 = false>
; __device__ __forceinline__ void gemm_phase(PG8_LAS unsigned char* lds, const Gemm g, const Sched& S, const Epi& E) {
;     ...
;             PG8_WAIT_V(8); PG8_WAIT_L(0); PG8_BAR; PG8_MMA(1, 0, At, B0); PG8_MMA(1, 1, At, B1); PG8_BAR; PG8_SCHED;
;             PG8_LDB(B0, 1, 0); PG8_LDB(B1, 1, 1); PG8_SCHED; PG8_LDA(At, 1, 0); PG8_STAGE(PG8_SA(0, 1), a2 + hstep, voffA);
;             PG8_WAIT_V(8); PG8_WAIT_L(0); PG8_BAR; PG8_MMA(0, 0, At, B0); PG8_MMA(0, 1, At, B1); PG8_BAR; PG8_SCHED;
	v_mfma_f32_16x16x32_bf16 v[64:67], v[132:135], v[204:207], 0
	v_mfma_f32_16x16x32_bf16 v[60:63], v[158:161], v[204:207], 0
	v_mfma_f32_16x16x32_bf16 v[48:51], v[132:135], v[212:215], 0
	v_mfma_f32_16x16x32_bf16 v[44:47], v[158:161], v[212:215], 0
	v_mfma_f32_16x16x32_bf16 v[32:35], v[132:135], v[220:223], 0
	v_mfma_f32_16x16x32_bf16 v[28:31], v[158:161], v[220:223], 0
	v_mfma_f32_16x16x32_bf16 v[16:19], v[132:135], v[228:231], 0
	v_mfma_f32_16x16x32_bf16 v[12:15], v[158:161], v[228:231], 0
	v_mfma_f32_16x16x32_bf16 v[64:67], v[136:139], v[208:211], v[64:67]
	v_mfma_f32_16x16x32_bf16 v[60:63], v[162:165], v[208:211], v[60:63]
	v_mfma_f32_16x16x32_bf16 v[48:51], v[136:139], v[216:219], v[48:51]
	v_mfma_f32_16x16x32_bf16 v[44:47], v[162:165], v[216:219], v[44:47]
	v_mfma_f32_16x16x32_bf16 v[32:35], v[136:139], v[224:227], v[32:35]
	v_mfma_f32_16x16x32_bf16 v[28:31], v[162:165], v[224:227], v[28:31]
	v_mfma_f32_16x16x32_bf16 v[16:19], v[136:139], v[232:235], v[16:19]
	v_mfma_f32_16x16x32_bf16 v[12:15], v[162:165], v[232:235], v[12:15]
	v_mfma_f32_16x16x32_bf16 v[56:59], v[188:191], v[204:207], 0
	v_mfma_f32_16x16x32_bf16 v[52:55], v[196:199], v[204:207], 0
	v_mfma_f32_16x16x32_bf16 v[40:43], v[188:191], v[212:215], 0
	v_mfma_f32_16x16x32_bf16 v[36:39], v[196:199], v[212:215], 0
	v_mfma_f32_16x16x32_bf16 v[24:27], v[188:191], v[220:223], 0
	v_mfma_f32_16x16x32_bf16 v[20:23], v[196:199], v[220:223], 0
	v_mfma_f32_16x16x32_bf16 v[8:11], v[188:191], v[228:231], 0
	v_mfma_f32_16x16x32_bf16 v[4:7], v[196:199], v[228:231], 0
	v_mfma_f32_16x16x32_bf16 v[56:59], v[192:195], v[208:211], v[56:59]
	v_mfma_f32_16x16x32_bf16 v[52:55], v[200:203], v[208:211], v[52:55]
	v_mfma_f32_16x16x32_bf16 v[40:43], v[192:195], v[216:219], v[40:43]
	v_mfma_f32_16x16x32_bf16 v[36:39], v[200:203], v[216:219], v[36:39]
	v_mfma_f32_16x16x32_bf16 v[24:27], v[192:195], v[224:227], v[24:27]
	v_mfma_f32_16x16x32_bf16 v[20:23], v[200:203], v[224:227], v[20:23]
	v_mfma_f32_16x16x32_bf16 v[8:11], v[192:195], v[232:235], v[8:11]
	v_mfma_f32_16x16x32_bf16 v[4:7], v[200:203], v[232:235], v[4:7]
	s_barrier
	s_setprio 0
	s_add_i32 s65, 0, 0x18000
	s_add_i32 s66, 0, 0x1c000
	ds_read_b128 v[132:135], v242
	ds_read_b128 v[136:139], v242 offset:1024
	ds_read_b128 v[158:161], v242 offset:2048
	ds_read_b128 v[162:165], v242 offset:3072
	ds_read_b128 v[188:191], v243
	ds_read_b128 v[192:195], v243 offset:1024
	ds_read_b128 v[196:199], v243 offset:2048
	ds_read_b128 v[200:203], v243 offset:3072
	s_add_u32 s26, s26, 0x80000
	s_addc_u32 s27, s27, 0
	s_mov_b32 m0, s35
	ds_read_b128 v[204:207], v187 offset:32768
	ds_read_b128 v[208:211], v187 offset:33792
	ds_read_b128 v[212:215], v187 offset:34816
	ds_read_b128 v[216:219], v187 offset:35840
	ds_read_b128 v[220:223], v187 offset:36864
	ds_read_b128 v[224:227], v187 offset:37888
	ds_read_b128 v[228:231], v187 offset:38912
	ds_read_b128 v[232:235], v187 offset:39936
	global_load_lds_dwordx4 v0, s[26:27]
	s_mov_b32 m0, s42
	s_nop 0
	global_load_lds_dwordx4 v150, s[26:27]
	s_waitcnt vmcnt(8)
	s_waitcnt lgkmcnt(0)
	s_setprio 1
	s_barrier
	v_mfma_f32_16x16x32_bf16 v[128:131], v[132:135], v[204:207], v[128:131]
	v_mfma_f32_16x16x32_bf16 v[124:127], v[158:161], v[204:207], v[124:127]
	v_mfma_f32_16x16x32_bf16 v[112:115], v[132:135], v[212:215], v[112:115]
	v_mfma_f32_16x16x32_bf16 v[108:111], v[158:161], v[212:215], v[108:111]
	v_mfma_f32_16x16x32_bf16 v[96:99], v[132:135], v[220:223], v[96:99]
	v_mfma_f32_16x16x32_bf16 v[92:95], v[158:161], v[220:223], v[92:95]
	v_mfma_f32_16x16x32_bf16 v[80:83], v[132:135], v[228:231], v[80:83]
	v_mfma_f32_16x16x32_bf16 v[76:79], v[158:161], v[228:231], v[76:79]
	v_mfma_f32_16x16x32_bf16 v[128:131], v[136:139], v[208:211], v[128:131]
	v_mfma_f32_16x16x32_bf16 v[124:127], v[162:165], v[208:211], v[124:127]
	v_mfma_f32_16x16x32_bf16 v[112:115], v[136:139], v[216:219], v[112:115]
	v_mfma_f32_16x16x32_bf16 v[108:111], v[162:165], v[216:219], v[108:111]
	v_mfma_f32_16x16x32_bf16 v[96:99], v[136:139], v[224:227], v[96:99]
	v_mfma_f32_16x16x32_bf16 v[92:95], v[162:165], v[224:227], v[92:95]
	v_mfma_f32_16x16x32_bf16 v[80:83], v[136:139], v[232:235], v[80:83]
	v_mfma_f32_16x16x32_bf16 v[76:79], v[162:165], v[232:235], v[76:79]
	v_mfma_f32_16x16x32_bf16 v[120:123], v[188:191], v[204:207], v[120:123]
	v_mfma_f32_16x16x32_bf16 v[116:119], v[196:199], v[204:207], v[116:119]
	v_mfma_f32_16x16x32_bf16 v[104:107], v[188:191], v[212:215], v[104:107]
	v_mfma_f32_16x16x32_bf16 v[100:103], v[196:199], v[212:215], v[100:103]
	v_mfma_f32_16x16x32_bf16 v[88:91], v[188:191], v[220:223], v[88:91]
	v_mfma_f32_16x16x32_bf16 v[84:87], v[196:199], v[220:223], v[84:87]
	v_mfma_f32_16x16x32_bf16 v[72:75], v[188:191], v[228:231], v[72:75]
	v_mfma_f32_16x16x32_bf16 v[68:71], v[196:199], v[228:231], v[68:71]
	v_mfma_f32_16x16x32_bf16 v[120:123], v[192:195], v[208:211], v[120:123]
	v_mfma_f32_16x16x32_bf16 v[116:119], v[200:203], v[208:211], v[116:119]
	v_mfma_f32_16x16x32_bf16 v[104:107], v[192:195], v[216:219], v[104:107]
	v_mfma_f32_16x16x32_bf16 v[100:103], v[200:203], v[216:219], v[100:103]
	v_mfma_f32_16x16x32_bf16 v[88:91], v[192:195], v[224:227], v[88:91]
	v_mfma_f32_16x16x32_bf16 v[84:87], v[200:203], v[224:227], v[84:87]
	v_mfma_f32_16x16x32_bf16 v[72:75], v[192:195], v[232:235], v[72:75]
	v_mfma_f32_16x16x32_bf16 v[68:71], v[200:203], v[232:235], v[68:71]
	s_barrier
; #define PG8_STAGE(bufoff, gbase, voff) do { _Pragma("unroll") for (int _i = 0; _i < 2; ++_i) \
;         __builtin_amdgcn_global_load_lds((const unsigned*)((const char*)(gbase) + (voff)[_i]), (PG8_LAS unsigned*)(lds + (bufoff) + ldsw + _i * 8192), 16, 0, 0); } while (0)
; #define PG8_LDA(dst, b, h) do { _Pragma("unroll") for (int m = 0; m < 4; ++m) _Pragma("unroll") for (int k = 0; k < 2; ++k) dst[m][k] = *(const PG8_LAS bf16x8*)(lds + PG8_SA(b, h) + aoff + m * 2048 + k * 1024); } while (0)
; #define PG8_MMA(ai, bj, At, Bt) do { __builtin_amdgcn_s_setprio(1); _Pragma("unroll") for (int m = 0; m < 4; ++m) _Pragma("unroll") for (int n = 0; n < 2; ++n) _Pragma("unroll") for (int k = 0; k < 2; ++k) \
;         acc[ai][bj][m][n] = __builtin_amdgcn_mfma_f32_16x16x32_bf16(Bt[n][k], At[m][k], acc[ai][bj][m][n], 0, 0, 0); __builtin_amdgcn_s_setprio(0); } while (0)
; #define PG8_WAIT_V(n) asm volatile("s_waitcnt vmcnt(" #n ")" ::: "memory")
; #define PG8_WAIT_L(n) asm volatile("s_waitcnt lgkmcnt(" #n ")" ::: "memory")
; #define PG8_BAR __builtin_amdgcn_s_barrier()
; #define PG8_SCHED __builtin_amdgcn_sched_barrier(0)
; template <class Epi, class Sched, bool ALIGN_EPI = false, bool SP2 = false>
; __device__ __forceinline__ void gemm_phase(PG8_LAS unsigned char* lds, const Gemm g, const Sched& S, const Epi& E) {
;     ...
;             PG8_LDA(At, 1, 1); PG8_STAGE(PG8_SB(1, 0), b3, voffB); PG8_STAGE(PG8_SB(1, 1), b3 + hstep, voffB); PG8_STAGE(PG8_SA(1, 0), a3, voffA);
;             PG8_WAIT_V(8); PG8_WAIT_L(0); PG8_BAR; PG8_MMA(1, 0, At, B0); PG8_MMA(1, 1, At, B1); PG8_BAR; PG8_SCHED;
	s_setprio 0
	s_add_i32 s26, s65, s31
	s_mov_b32 m0, s26
	ds_read_b128 v[204:207], v187 offset:49152
	ds_read_b128 v[208:211], v187 offset:50176
	ds_read_b128 v[212:215], v187 offset:51200
	ds_read_b128 v[216:219], v187 offset:52224
	ds_read_b128 v[220:223], v187 offset:53248
	ds_read_b128 v[224:227], v187 offset:54272
	ds_read_b128 v[228:231], v187 offset:55296
	ds_read_b128 v[232:235], v187 offset:56320
	s_add_u32 vcc_lo, s24, 0x80
	s_addc_u32 vcc_hi, s25, 0
	global_load_lds_dwordx4 v2, vcc
	s_add_i32 m0, s26, 0x2000
	s_add_u32 s24, s24, 0x80080
	s_addc_u32 s25, s25, 0
	s_add_i32 s26, s66, s31
	s_add_u32 vcc_lo, s24, 0xfff80000
	s_addc_u32 vcc_hi, s25, -1
	global_load_lds_dwordx4 v152, vcc
	s_mov_b32 m0, s26
	s_nop 0
	global_load_lds_dwordx4 v2, s[24:25]
	s_add_i32 m0, s26, 0x2000
	s_nop 0
	global_load_lds_dwordx4 v152, s[24:25]
	v_lshl_add_u64 v[166:167], v[238:239], 0, s[36:37]
	s_mov_b32 m0, s44
	s_nop 0
	global_load_lds_dwordx4 v[166:167], off
	v_lshl_add_u64 v[166:167], v[240:241], 0, s[36:37]
	s_mov_b32 m0, s45
	s_nop 0
	global_load_lds_dwordx4 v[166:167], off
	s_waitcnt vmcnt(8)
	s_waitcnt lgkmcnt(0)
	s_setprio 1
	s_barrier
	v_mfma_f32_16x16x32_bf16 v[64:67], v[132:135], v[204:207], v[64:67]
	v_mfma_f32_16x16x32_bf16 v[60:63], v[158:161], v[204:207], v[60:63]
	v_mfma_f32_16x16x32_bf16 v[48:51], v[132:135], v[212:215], v[48:51]
	v_mfma_f32_16x16x32_bf16 v[44:47], v[158:161], v[212:215], v[44:47]
	v_mfma_f32_16x16x32_bf16 v[32:35], v[132:135], v[220:223], v[32:35]
	v_mfma_f32_16x16x32_bf16 v[28:31], v[158:161], v[220:223], v[28:31]
	v_mfma_f32_16x16x32_bf16 v[16:19], v[132:135], v[228:231], v[16:19]
	v_mfma_f32_16x16x32_bf16 v[12:15], v[158:161], v[228:231], v[12:15]
	v_mfma_f32_16x16x32_bf16 v[64:67], v[136:139], v[208:211], v[64:67]
	v_mfma_f32_16x16x32_bf16 v[60:63], v[162:165], v[208:211], v[60:63]
	v_mfma_f32_16x16x32_bf16 v[48:51], v[136:139], v[216:219], v[48:51]
	v_mfma_f32_16x16x32_bf16 v[44:47], v[162:165], v[216:219], v[44:47]
	v_mfma_f32_16x16x32_bf16 v[32:35], v[136:139], v[224:227], v[32:35]
	v_mfma_f32_16x16x32_bf16 v[28:31], v[162:165], v[224:227], v[28:31]
	v_mfma_f32_16x16x32_bf16 v[16:19], v[136:139], v[232:235], v[16:19]
	v_mfma_f32_16x16x32_bf16 v[12:15], v[162:165], v[232:235], v[12:15]
	v_mfma_f32_16x16x32_bf16 v[56:59], v[188:191], v[204:207], v[56:59]
	v_mfma_f32_16x16x32_bf16 v[52:55], v[196:199], v[204:207], v[52:55]
	v_mfma_f32_16x16x32_bf16 v[40:43], v[188:191], v[212:215], v[40:43]
	v_mfma_f32_16x16x32_bf16 v[36:39], v[196:199], v[212:215], v[36:39]
	v_mfma_f32_16x16x32_bf16 v[24:27], v[188:191], v[220:223], v[24:27]
	v_mfma_f32_16x16x32_bf16 v[20:23], v[196:199], v[220:223], v[20:23]
	v_mfma_f32_16x16x32_bf16 v[8:11], v[188:191], v[228:231], v[8:11]
	v_mfma_f32_16x16x32_bf16 v[4:7], v[196:199], v[228:231], v[4:7]
	v_mfma_f32_16x16x32_bf16 v[56:59], v[192:195], v[208:211], v[56:59]
	v_mfma_f32_16x16x32_bf16 v[52:55], v[200:203], v[208:211], v[52:55]
	v_mfma_f32_16x16x32_bf16 v[40:43], v[192:195], v[216:219], v[40:43]
	v_mfma_f32_16x16x32_bf16 v[36:39], v[200:203], v[216:219], v[36:39]
	v_mfma_f32_16x16x32_bf16 v[24:27], v[192:195], v[224:227], v[24:27]
	v_mfma_f32_16x16x32_bf16 v[20:23], v[200:203], v[224:227], v[20:23]
	v_mfma_f32_16x16x32_bf16 v[8:11], v[192:195], v[232:235], v[8:11]
	v_mfma_f32_16x16x32_bf16 v[4:7], v[200:203], v[232:235], v[4:7]
	s_barrier
	s_setprio 0
	s_add_i32 s64, s64, 2
	s_add_u32 s22, s22, 0x100
	s_addc_u32 s23, s23, 0
	s_add_u32 s57, s57, 0x100
	s_addc_u32 s63, s63, 0
	s_cmp_gt_u32 s64, 29

; #define PG8_STAGE(bufoff, gbase, voff) do { _Pragma("unroll") for (int _i = 0; _i < 2; ++_i) \
;         __builtin_amdgcn_global_load_lds((const unsigned*)((const char*)(gbase) + (voff)[_i]), (PG8_LAS unsigned*)(lds + (bufoff) + ldsw + _i * 8192), 16, 0, 0); } while (0)
; #define PG8_LDA(dst, b, h) do { _Pragma("unroll") for (int m = 0; m < 4; ++m) _Pragma("unroll") for (int k = 0; k < 2; ++k) dst[m][k] = *(const PG8_LAS bf16x8*)(lds + PG8_SA(b, h) + aoff + m * 2048 + k * 1024); } while (0)
; #define PG8_LDB(dst, b, h) do { _Pragma("unroll") for (int n = 0; n < 2; ++n) _Pragma("unroll") for (int k = 0; k < 2; ++k) dst[n][k] = *(const PG8_LAS bf16x8*)(lds + PG8_SB(b, h) + boff + n * 2048 + k * 1024); } while (0)
; #define PG8_WAIT_V(n) asm volatile("s_waitcnt vmcnt(" #n ")" ::: "memory")
; #define PG8_WAIT_L(n) asm volatile("s_waitcnt lgkmcnt(" #n ")" ::: "memory")
; #define PG8_BAR __builtin_amdgcn_s_barrier()
; #define PG8_SCHED __builtin_amdgcn_sched_barrier(0)
; template <class Epi, class Sched, bool ALIGN_EPI = false, bool SP2 = false>
; __device__ __forceinline__ void gemm_phase(PG8_LAS unsigned char* lds, const Gemm g, const Sched& S, const Epi& E) {
;     ...
;         const char* nA = has_next ? (const char*)g.A + (size_t)nxt.pm * tstep : cA; const char* nB = has_next ? (const char*)g.Bt + (size_t)nxt.pn * tstep : cB;
;         for (int t = 0; t < nt; t += 2) {
;             const bool last = (t == nt - 2);
;             const char* a1 = cA + (size_t)(t + 1) * kstep;
;             const char* a2 = last ? nA : cA + (size_t)(t + 2) * kstep; const char* b2 = last ? nB : cB + (size_t)(t + 2) * kstep;
;             const char* a3 = a2 + kstep; const char* b3 = b2 + kstep;
;             if (last && has_next) S.a_ready(nxt);
;             if constexpr (SP2) {
;             PG8_LDB(B0, 0, 0); PG8_LDB(B1, 0, 1); PG8_SCHED; PG8_LDA(At, 0, 0); PG8_STAGE(PG8_SA(1, 1), a1 + hstep, voffA);
;             PG8_WAIT_V(8); PG8_WAIT_L(0); PG8_BAR; PG8_MMA(0, 0, At, B0); PG8_MMA(0, 1, At, B1); PG8_BAR; PG8_SCHED;
;             PG8_LDA(At, 0, 1); PG8_STAGE(PG8_SB(0, 0), b2, voffB); PG8_STAGE(PG8_SB(0, 1), b2 + hstep, voffB); PG8_STAGE(PG8_SA(0, 0), a2, voffA);
;             PG8_WAIT_V(8); PG8_WAIT_L(0); PG8_BAR; PG8_MMA(1, 0, At, B0); PG8_MMA(1, 1, At, B1); PG8_BAR; PG8_SCHED;
.LBB0_566:
	s_ashr_i32 s11, s10, 31
	s_lshl_b64 s[12:13], s[10:11], 20
	s_add_u32 s12, s46, s12
	s_addc_u32 s13, s47, s13
	s_and_b64 s[14:15], s[2:3], exec
	s_cselect_b32 s11, s13, s19
	s_cselect_b32 s45, s12, s18
	s_ashr_i32 s9, s8, 31
	s_lshl_b64 s[14:15], s[8:9], 20
	s_add_u32 s14, s25, s14
	s_addc_u32 s15, s26, s15
	s_and_b64 s[22:23], s[2:3], exec
	s_cselect_b32 s9, s15, s21
	s_cselect_b32 s50, s14, s20
	s_add_u32 s18, s18, 0x80080
	s_addc_u32 s19, s19, 0
	s_add_u32 s51, s20, 0x100
	s_addc_u32 s56, s21, 0
	s_mov_b32 s57, -2
	v_add_u32_e32 v166, 0x10000, v153
	v_add_u32_e32 v167, 0x14000, v153
	v_add_u32_e32 v252, 0x18000, v153
	v_add_u32_e32 v253, 0x1c000, v153
	s_add_u32 s20, s18, 0xfff80080
	s_addc_u32 s21, s19, -1
	s_add_i32 s63, 0, 0x10000
	s_cmp_eq_u32 s57, 28
	s_cselect_b32 s23, s11, s21
	s_cselect_b32 s22, s45, s20
	s_cselect_b32 s21, s9, s56
	s_cselect_b32 s20, s50, s51
	s_add_i32 s66, 0, 0x14000
	ds_read_b128 v[184:187], v166
	ds_read_b128 v[188:191], v166 offset:1024
	ds_read_b128 v[192:195], v166 offset:2048
	ds_read_b128 v[196:199], v166 offset:3072
	ds_read_b128 v[200:203], v167
	ds_read_b128 v[204:207], v167 offset:1024
	ds_read_b128 v[208:211], v167 offset:2048
	ds_read_b128 v[212:215], v167 offset:3072
	s_add_i32 m0, s29, 0xc000
	ds_read_b128 v[216:219], v155
	ds_read_b128 v[220:223], v155 offset:1024
	ds_read_b128 v[224:227], v155 offset:2048
	ds_read_b128 v[228:231], v155 offset:3072
	ds_read_b128 v[232:235], v155 offset:4096
	ds_read_b128 v[236:239], v155 offset:5120
	ds_read_b128 v[240:243], v155 offset:6144
	ds_read_b128 v[244:247], v155 offset:7168
	global_load_lds_dwordx4 v136, s[18:19]
	s_add_i32 m0, s29, 0xe000
	s_nop 0
	global_load_lds_dwordx4 v138, s[18:19]
	s_waitcnt vmcnt(24)
	s_waitcnt lgkmcnt(0)
	s_setprio 1
	s_barrier
	v_mfma_f32_16x16x32_bf16 v[128:131], v[184:187], v[216:219], 0
	v_mfma_f32_16x16x32_bf16 v[120:123], v[192:195], v[216:219], 0
	v_mfma_f32_16x16x32_bf16 v[112:115], v[184:187], v[224:227], 0
	v_mfma_f32_16x16x32_bf16 v[104:107], v[192:195], v[224:227], 0
	v_mfma_f32_16x16x32_bf16 v[96:99], v[184:187], v[232:235], 0
	v_mfma_f32_16x16x32_bf16 v[88:91], v[192:195], v[232:235], 0
	v_mfma_f32_16x16x32_bf16 v[80:83], v[184:187], v[240:243], 0
	v_mfma_f32_16x16x32_bf16 v[72:75], v[192:195], v[240:243], 0
	v_mfma_f32_16x16x32_bf16 v[128:131], v[188:191], v[220:223], v[128:131]
	v_mfma_f32_16x16x32_bf16 v[120:123], v[196:199], v[220:223], v[120:123]
	v_mfma_f32_16x16x32_bf16 v[112:115], v[188:191], v[228:231], v[112:115]
	v_mfma_f32_16x16x32_bf16 v[104:107], v[196:199], v[228:231], v[104:107]
	v_mfma_f32_16x16x32_bf16 v[96:99], v[188:191], v[236:239], v[96:99]
	v_mfma_f32_16x16x32_bf16 v[88:91], v[196:199], v[236:239], v[88:91]
	v_mfma_f32_16x16x32_bf16 v[80:83], v[188:191], v[244:247], v[80:83]
	v_mfma_f32_16x16x32_bf16 v[72:75], v[196:199], v[244:247], v[72:75]
	v_mfma_f32_16x16x32_bf16 v[124:127], v[200:203], v[216:219], 0
	v_mfma_f32_16x16x32_bf16 v[116:119], v[208:211], v[216:219], 0
	v_mfma_f32_16x16x32_bf16 v[108:111], v[200:203], v[224:227], 0
	v_mfma_f32_16x16x32_bf16 v[100:103], v[208:211], v[224:227], 0
	v_mfma_f32_16x16x32_bf16 v[92:95], v[200:203], v[232:235], 0
	v_mfma_f32_16x16x32_bf16 v[84:87], v[208:211], v[232:235], 0
	v_mfma_f32_16x16x32_bf16 v[76:79], v[200:203], v[240:243], 0
	v_mfma_f32_16x16x32_bf16 v[68:71], v[208:211], v[240:243], 0
	v_mfma_f32_16x16x32_bf16 v[124:127], v[204:207], v[220:223], v[124:127]
	v_mfma_f32_16x16x32_bf16 v[116:119], v[212:215], v[220:223], v[116:119]
	v_mfma_f32_16x16x32_bf16 v[108:111], v[204:207], v[228:231], v[108:111]
	v_mfma_f32_16x16x32_bf16 v[100:103], v[212:215], v[228:231], v[100:103]
	v_mfma_f32_16x16x32_bf16 v[92:95], v[204:207], v[236:239], v[92:95]
	v_mfma_f32_16x16x32_bf16 v[84:87], v[212:215], v[236:239], v[84:87]
	v_mfma_f32_16x16x32_bf16 v[76:79], v[204:207], v[244:247], v[76:79]
	v_mfma_f32_16x16x32_bf16 v[68:71], v[212:215], v[244:247], v[68:71]
	s_barrier
	s_setprio 0
	s_add_i32 s63, s63, s27
	s_mov_b32 m0, s63
	ds_read_b128 v[216:219], v155 offset:16384
	ds_read_b128 v[220:223], v155 offset:17408
	ds_read_b128 v[224:227], v155 offset:18432
	ds_read_b128 v[228:231], v155 offset:19456
	ds_read_b128 v[232:235], v155 offset:20480
	ds_read_b128 v[236:239], v155 offset:21504
	ds_read_b128 v[240:243], v155 offset:22528
	ds_read_b128 v[244:247], v155 offset:23552
	global_load_lds_dwordx4 v2, s[20:21]
	s_add_i32 m0, s63, 0x2000
	s_add_u32 s64, s20, 0x80000
	s_addc_u32 s65, s21, 0
	s_add_i32 s63, s66, s27
	global_load_lds_dwordx4 v0, s[20:21]
	s_mov_b32 m0, s63
	v_lshl_add_u64 v[250:251], s[22:23], 0, v[132:133]
	global_load_lds_dwordx4 v2, s[64:65]
	s_add_i32 m0, s63, 0x2000
	s_nop 0
	global_load_lds_dwordx4 v0, s[64:65]
	v_lshl_add_u64 v[248:249], s[22:23], 0, v[134:135]
	s_mov_b32 m0, s29
	s_nop 0
	global_load_lds_dwordx4 v[248:249], off
	s_mov_b32 m0, s30
	s_nop 0
	global_load_lds_dwordx4 v[250:251], off
	s_waitcnt vmcnt(8)
	s_waitcnt lgkmcnt(0)
	s_setprio 1
	s_barrier
; #define PG8_STAGE(bufoff, gbase, voff) do { _Pragma("unroll") for (int _i = 0; _i < 2; ++_i) \
;         __builtin_amdgcn_global_load_lds((const unsigned*)((const char*)(gbase) + (voff)[_i]), (PG8_LAS unsigned*)(lds + (bufoff) + ldsw + _i * 8192), 16, 0, 0); } while (0)
; #define PG8_LDA(dst, b, h) do { _Pragma("unroll") for (int m = 0; m < 4; ++m) _Pragma("unroll") for (int k = 0; k < 2; ++k) dst[m][k] = *(const PG8_LAS bf16x8*)(lds + PG8_SA(b, h) + aoff + m * 2048 + k * 1024); } while (0)
; #define PG8_LDB(dst, b, h) do { _Pragma("unroll") for (int n = 0; n < 2; ++n) _Pragma("unroll") for (int k = 0; k < 2; ++k) dst[n][k] = *(const PG8_LAS bf16x8*)(lds + PG8_SB(b, h) + boff + n * 2048 + k * 1024); } while (0)
; #define PG8_MMA(ai, bj, At, Bt) do { __builtin_amdgcn_s_setprio(1); _Pragma("unroll") for (int m = 0; m < 4; ++m) _Pragma("unroll") for (int n = 0; n < 2; ++n) _Pragma("unroll") for (int k = 0; k < 2; ++k) \
;         acc[ai][bj][m][n] = __builtin_amdgcn_mfma_f32_16x16x32_bf16(Bt[n][k], At[m][k], acc[ai][bj][m][n], 0, 0, 0); __builtin_amdgcn_s_setprio(0); } while (0)
; #define PG8_WAIT_V(n) asm volatile("s_waitcnt vmcnt(" #n ")" ::: "memory")
; #define PG8_WAIT_L(n) asm volatile("s_waitcnt lgkmcnt(" #n ")" ::: "memory")
; #define PG8_BAR __builtin_amdgcn_s_barrier()
; #define PG8_SCHED __builtin_amdgcn_sched_barrier(0)
; template <class Epi, class Sched, bool ALIGN_EPI = false, bool SP2 = false>
; __device__ __forceinline__ void gemm_phase(PG8_LAS unsigned char* lds, const Gemm g, const Sched& S, const Epi& E) {
;     ...
;             PG8_WAIT_V(8); PG8_WAIT_L(0); PG8_BAR; PG8_MMA(1, 0, At, B0); PG8_MMA(1, 1, At, B1); PG8_BAR; PG8_SCHED;
;             PG8_LDB(B0, 1, 0); PG8_LDB(B1, 1, 1); PG8_SCHED; PG8_LDA(At, 1, 0); PG8_STAGE(PG8_SA(0, 1), a2 + hstep, voffA);
;             PG8_WAIT_V(8); PG8_WAIT_L(0); PG8_BAR; PG8_MMA(0, 0, At, B0); PG8_MMA(0, 1, At, B1); PG8_BAR; PG8_SCHED;
	v_mfma_f32_16x16x32_bf16 v[64:67], v[184:187], v[216:219], 0
	v_mfma_f32_16x16x32_bf16 v[56:59], v[192:195], v[216:219], 0
	v_mfma_f32_16x16x32_bf16 v[48:51], v[184:187], v[224:227], 0
	v_mfma_f32_16x16x32_bf16 v[40:43], v[192:195], v[224:227], 0
	v_mfma_f32_16x16x32_bf16 v[32:35], v[184:187], v[232:235], 0
	v_mfma_f32_16x16x32_bf16 v[24:27], v[192:195], v[232:235], 0
	v_mfma_f32_16x16x32_bf16 v[16:19], v[184:187], v[240:243], 0
	v_mfma_f32_16x16x32_bf16 v[8:11], v[192:195], v[240:243], 0
	v_mfma_f32_16x16x32_bf16 v[64:67], v[188:191], v[220:223], v[64:67]
	v_mfma_f32_16x16x32_bf16 v[56:59], v[196:199], v[220:223], v[56:59]
	v_mfma_f32_16x16x32_bf16 v[48:51], v[188:191], v[228:231], v[48:51]
	v_mfma_f32_16x16x32_bf16 v[40:43], v[196:199], v[228:231], v[40:43]
	v_mfma_f32_16x16x32_bf16 v[32:35], v[188:191], v[236:239], v[32:35]
	v_mfma_f32_16x16x32_bf16 v[24:27], v[196:199], v[236:239], v[24:27]
	v_mfma_f32_16x16x32_bf16 v[16:19], v[188:191], v[244:247], v[16:19]
	v_mfma_f32_16x16x32_bf16 v[8:11], v[196:199], v[244:247], v[8:11]
	v_mfma_f32_16x16x32_bf16 v[60:63], v[200:203], v[216:219], 0
	v_mfma_f32_16x16x32_bf16 v[52:55], v[208:211], v[216:219], 0
	v_mfma_f32_16x16x32_bf16 v[44:47], v[200:203], v[224:227], 0
	v_mfma_f32_16x16x32_bf16 v[36:39], v[208:211], v[224:227], 0
	v_mfma_f32_16x16x32_bf16 v[28:31], v[200:203], v[232:235], 0
	v_mfma_f32_16x16x32_bf16 v[20:23], v[208:211], v[232:235], 0
	v_mfma_f32_16x16x32_bf16 v[12:15], v[200:203], v[240:243], 0
	v_mfma_f32_16x16x32_bf16 v[4:7], v[208:211], v[240:243], 0
	v_mfma_f32_16x16x32_bf16 v[60:63], v[204:207], v[220:223], v[60:63]
	v_mfma_f32_16x16x32_bf16 v[52:55], v[212:215], v[220:223], v[52:55]
	v_mfma_f32_16x16x32_bf16 v[44:47], v[204:207], v[228:231], v[44:47]
	v_mfma_f32_16x16x32_bf16 v[36:39], v[212:215], v[228:231], v[36:39]
	v_mfma_f32_16x16x32_bf16 v[28:31], v[204:207], v[236:239], v[28:31]
	v_mfma_f32_16x16x32_bf16 v[20:23], v[212:215], v[236:239], v[20:23]
	v_mfma_f32_16x16x32_bf16 v[12:15], v[204:207], v[244:247], v[12:15]
	v_mfma_f32_16x16x32_bf16 v[4:7], v[212:215], v[244:247], v[4:7]
	s_barrier
	s_setprio 0
	s_add_i32 s63, 0, 0x18000
	s_add_i32 s64, 0, 0x1c000
	ds_read_b128 v[184:187], v252
	ds_read_b128 v[188:191], v252 offset:1024
	ds_read_b128 v[192:195], v252 offset:2048
	ds_read_b128 v[196:199], v252 offset:3072
	ds_read_b128 v[200:203], v253
	ds_read_b128 v[204:207], v253 offset:1024
	ds_read_b128 v[208:211], v253 offset:2048
	ds_read_b128 v[212:215], v253 offset:3072
	s_add_u32 s22, s22, 0x80000
	s_addc_u32 s23, s23, 0
	s_mov_b32 m0, s31
	ds_read_b128 v[216:219], v155 offset:32768
	ds_read_b128 v[220:223], v155 offset:33792
	ds_read_b128 v[224:227], v155 offset:34816
	ds_read_b128 v[228:231], v155 offset:35840
	ds_read_b128 v[232:235], v155 offset:36864
	ds_read_b128 v[236:239], v155 offset:37888
	ds_read_b128 v[240:243], v155 offset:38912
	ds_read_b128 v[244:247], v155 offset:39936
	global_load_lds_dwordx4 v134, s[22:23]
	s_mov_b32 m0, s34
	s_nop 0
	global_load_lds_dwordx4 v132, s[22:23]
	s_waitcnt vmcnt(8)
	s_waitcnt lgkmcnt(0)
	s_setprio 1
	s_barrier
	v_mfma_f32_16x16x32_bf16 v[128:131], v[184:187], v[216:219], v[128:131]
	v_mfma_f32_16x16x32_bf16 v[120:123], v[192:195], v[216:219], v[120:123]
	v_mfma_f32_16x16x32_bf16 v[112:115], v[184:187], v[224:227], v[112:115]
	v_mfma_f32_16x16x32_bf16 v[104:107], v[192:195], v[224:227], v[104:107]
	v_mfma_f32_16x16x32_bf16 v[96:99], v[184:187], v[232:235], v[96:99]
	v_mfma_f32_16x16x32_bf16 v[88:91], v[192:195], v[232:235], v[88:91]
	v_mfma_f32_16x16x32_bf16 v[80:83], v[184:187], v[240:243], v[80:83]
	v_mfma_f32_16x16x32_bf16 v[72:75], v[192:195], v[240:243], v[72:75]
	v_mfma_f32_16x16x32_bf16 v[128:131], v[188:191], v[220:223], v[128:131]
	v_mfma_f32_16x16x32_bf16 v[120:123], v[196:199], v[220:223], v[120:123]
	v_mfma_f32_16x16x32_bf16 v[112:115], v[188:191], v[228:231], v[112:115]
	v_mfma_f32_16x16x32_bf16 v[104:107], v[196:199], v[228:231], v[104:107]
	v_mfma_f32_16x16x32_bf16 v[96:99], v[188:191], v[236:239], v[96:99]
	v_mfma_f32_16x16x32_bf16 v[88:91], v[196:199], v[236:239], v[88:91]
	v_mfma_f32_16x16x32_bf16 v[80:83], v[188:191], v[244:247], v[80:83]
	v_mfma_f32_16x16x32_bf16 v[72:75], v[196:199], v[244:247], v[72:75]
	v_mfma_f32_16x16x32_bf16 v[124:127], v[200:203], v[216:219], v[124:127]
	v_mfma_f32_16x16x32_bf16 v[116:119], v[208:211], v[216:219], v[116:119]
	v_mfma_f32_16x16x32_bf16 v[108:111], v[200:203], v[224:227], v[108:111]
	v_mfma_f32_16x16x32_bf16 v[100:103], v[208:211], v[224:227], v[100:103]
	v_mfma_f32_16x16x32_bf16 v[92:95], v[200:203], v[232:235], v[92:95]
	v_mfma_f32_16x16x32_bf16 v[84:87], v[208:211], v[232:235], v[84:87]
	v_mfma_f32_16x16x32_bf16 v[76:79], v[200:203], v[240:243], v[76:79]
	v_mfma_f32_16x16x32_bf16 v[68:71], v[208:211], v[240:243], v[68:71]
	v_mfma_f32_16x16x32_bf16 v[124:127], v[204:207], v[220:223], v[124:127]
	v_mfma_f32_16x16x32_bf16 v[116:119], v[212:215], v[220:223], v[116:119]
	v_mfma_f32_16x16x32_bf16 v[108:111], v[204:207], v[228:231], v[108:111]
	v_mfma_f32_16x16x32_bf16 v[100:103], v[212:215], v[228:231], v[100:103]
	v_mfma_f32_16x16x32_bf16 v[92:95], v[204:207], v[236:239], v[92:95]
	v_mfma_f32_16x16x32_bf16 v[84:87], v[212:215], v[236:239], v[84:87]
	v_mfma_f32_16x16x32_bf16 v[76:79], v[204:207], v[244:247], v[76:79]
	v_mfma_f32_16x16x32_bf16 v[68:71], v[212:215], v[244:247], v[68:71]
	s_barrier
; #define PG8_STAGE(bufoff, gbase, voff) do { _Pragma("unroll") for (int _i = 0; _i < 2; ++_i) \
;         __builtin_amdgcn_global_load_lds((const unsigned*)((const char*)(gbase) + (voff)[_i]), (PG8_LAS unsigned*)(lds + (bufoff) + ldsw + _i * 8192), 16, 0, 0); } while (0)
; #define PG8_LDA(dst, b, h) do { _Pragma("unroll") for (int m = 0; m < 4; ++m) _Pragma("unroll") for (int k = 0; k < 2; ++k) dst[m][k] = *(const PG8_LAS bf16x8*)(lds + PG8_SA(b, h) + aoff + m * 2048 + k * 1024); } while (0)
; #define PG8_MMA(ai, bj, At, Bt) do { __builtin_amdgcn_s_setprio(1); _Pragma("unroll") for (int m = 0; m < 4; ++m) _Pragma("unroll") for (int n = 0; n < 2; ++n) _Pragma("unroll") for (int k = 0; k < 2; ++k) \
;         acc[ai][bj][m][n] = __builtin_amdgcn_mfma_f32_16x16x32_bf16(Bt[n][k], At[m][k], acc[ai][bj][m][n], 0, 0, 0); __builtin_amdgcn_s_setprio(0); } while (0)
; #define PG8_WAIT_V(n) asm volatile("s_waitcnt vmcnt(" #n ")" ::: "memory")
; #define PG8_WAIT_L(n) asm volatile("s_waitcnt lgkmcnt(" #n ")" ::: "memory")
; #define PG8_BAR __builtin_amdgcn_s_barrier()
; #define PG8_SCHED __builtin_amdgcn_sched_barrier(0)
; template <class Epi, class Sched, bool ALIGN_EPI = false, bool SP2 = false>
; __device__ __forceinline__ void gemm_phase(PG8_LAS unsigned char* lds, const Gemm g, const Sched& S, const Epi& E) {
;     ...
;             PG8_LDA(At, 1, 1); PG8_STAGE(PG8_SB(1, 0), b3, voffB); PG8_STAGE(PG8_SB(1, 1), b3 + hstep, voffB); PG8_STAGE(PG8_SA(1, 0), a3, voffA);
;             PG8_WAIT_V(8); PG8_WAIT_L(0); PG8_BAR; PG8_MMA(1, 0, At, B0); PG8_MMA(1, 1, At, B1); PG8_BAR; PG8_SCHED;
	s_setprio 0
	s_add_i32 s22, s63, s27
	s_mov_b32 m0, s22
	ds_read_b128 v[216:219], v155 offset:49152
	ds_read_b128 v[220:223], v155 offset:50176
	ds_read_b128 v[224:227], v155 offset:51200
	ds_read_b128 v[228:231], v155 offset:52224
	ds_read_b128 v[232:235], v155 offset:53248
	ds_read_b128 v[236:239], v155 offset:54272
	ds_read_b128 v[240:243], v155 offset:55296
	ds_read_b128 v[244:247], v155 offset:56320
	s_add_u32 vcc_lo, s20, 0x80
	s_addc_u32 vcc_hi, s21, 0
	global_load_lds_dwordx4 v2, vcc
	s_add_i32 m0, s22, 0x2000
	s_add_u32 s20, s20, 0x80080
	s_addc_u32 s21, s21, 0
	s_add_i32 s22, s64, s27
	s_add_u32 vcc_lo, s20, 0xfff80000
	s_addc_u32 vcc_hi, s21, -1
	global_load_lds_dwordx4 v0, vcc
	s_mov_b32 m0, s22
	s_nop 0
	global_load_lds_dwordx4 v2, s[20:21]
	s_add_i32 m0, s22, 0x2000
	s_nop 0
	global_load_lds_dwordx4 v0, s[20:21]
	v_lshl_add_u64 v[150:151], v[248:249], 0, s[36:37]
	s_mov_b32 m0, s35
	s_nop 0
	global_load_lds_dwordx4 v[150:151], off
	v_lshl_add_u64 v[150:151], v[250:251], 0, s[36:37]
	s_mov_b32 m0, s42
	s_nop 0
	global_load_lds_dwordx4 v[150:151], off
	s_waitcnt vmcnt(8)
	s_waitcnt lgkmcnt(0)
	s_setprio 1
	s_barrier
	v_mfma_f32_16x16x32_bf16 v[64:67], v[184:187], v[216:219], v[64:67]
	v_mfma_f32_16x16x32_bf16 v[56:59], v[192:195], v[216:219], v[56:59]
	v_mfma_f32_16x16x32_bf16 v[48:51], v[184:187], v[224:227], v[48:51]
	v_mfma_f32_16x16x32_bf16 v[40:43], v[192:195], v[224:227], v[40:43]
	v_mfma_f32_16x16x32_bf16 v[32:35], v[184:187], v[232:235], v[32:35]
	v_mfma_f32_16x16x32_bf16 v[24:27], v[192:195], v[232:235], v[24:27]
	v_mfma_f32_16x16x32_bf16 v[16:19], v[184:187], v[240:243], v[16:19]
	v_mfma_f32_16x16x32_bf16 v[8:11], v[192:195], v[240:243], v[8:11]
	v_mfma_f32_16x16x32_bf16 v[64:67], v[188:191], v[220:223], v[64:67]
	v_mfma_f32_16x16x32_bf16 v[56:59], v[196:199], v[220:223], v[56:59]
	v_mfma_f32_16x16x32_bf16 v[48:51], v[188:191], v[228:231], v[48:51]
	v_mfma_f32_16x16x32_bf16 v[40:43], v[196:199], v[228:231], v[40:43]
	v_mfma_f32_16x16x32_bf16 v[32:35], v[188:191], v[236:239], v[32:35]
	v_mfma_f32_16x16x32_bf16 v[24:27], v[196:199], v[236:239], v[24:27]
	v_mfma_f32_16x16x32_bf16 v[16:19], v[188:191], v[244:247], v[16:19]
	v_mfma_f32_16x16x32_bf16 v[8:11], v[196:199], v[244:247], v[8:11]
	v_mfma_f32_16x16x32_bf16 v[60:63], v[200:203], v[216:219], v[60:63]
	v_mfma_f32_16x16x32_bf16 v[52:55], v[208:211], v[216:219], v[52:55]
	v_mfma_f32_16x16x32_bf16 v[44:47], v[200:203], v[224:227], v[44:47]
	v_mfma_f32_16x16x32_bf16 v[36:39], v[208:211], v[224:227], v[36:39]
	v_mfma_f32_16x16x32_bf16 v[28:31], v[200:203], v[232:235], v[28:31]
	v_mfma_f32_16x16x32_bf16 v[20:23], v[208:211], v[232:235], v[20:23]
	v_mfma_f32_16x16x32_bf16 v[12:15], v[200:203], v[240:243], v[12:15]
	v_mfma_f32_16x16x32_bf16 v[4:7], v[208:211], v[240:243], v[4:7]
	v_mfma_f32_16x16x32_bf16 v[60:63], v[204:207], v[220:223], v[60:63]
	v_mfma_f32_16x16x32_bf16 v[52:55], v[212:215], v[220:223], v[52:55]
	v_mfma_f32_16x16x32_bf16 v[44:47], v[204:207], v[228:231], v[44:47]
	v_mfma_f32_16x16x32_bf16 v[36:39], v[212:215], v[228:231], v[36:39]
	v_mfma_f32_16x16x32_bf16 v[28:31], v[204:207], v[236:239], v[28:31]
	v_mfma_f32_16x16x32_bf16 v[20:23], v[212:215], v[236:239], v[20:23]
	v_mfma_f32_16x16x32_bf16 v[12:15], v[204:207], v[244:247], v[12:15]
	v_mfma_f32_16x16x32_bf16 v[4:7], v[212:215], v[244:247], v[4:7]
	s_barrier
	s_setprio 0
	s_add_i32 s57, s57, 2
	s_add_u32 s18, s18, 0x100
	s_addc_u32 s19, s19, 0
	s_add_u32 s51, s51, 0x100
	s_addc_u32 s56, s56, 0
	s_cmp_gt_u32 s57, 29
